# attn-proj / lru-proj main epilogues: first-half gate-operand loads issued before the K-loop's closing barrier
# baseline (speedup 1.0000x reference)
; #define PG8_STAGE(bufoff, gbase, voff) do { _Pragma("unroll") for (int _i = 0; _i < 2; ++_i) \
;         __builtin_amdgcn_global_load_lds((const unsigned*)((const char*)(gbase) + (voff)[_i]), (PG8_LAS unsigned*)(lds + (bufoff) + ldsw + _i * 8192), 16, 0, 0); } while (0)
; #define PG8_LDA(dst, b, h) do { _Pragma("unroll") for (int m = 0; m < 4; ++m) _Pragma("unroll") for (int k = 0; k < 2; ++k) dst[m][k] = *(const PG8_LAS bf16x8*)(lds + PG8_SA(b, h) + aoff + m * 2048 + k * 1024); } while (0)
; #define PG8_LDB(dst, b, h) do { _Pragma("unroll") for (int n = 0; n < 2; ++n) _Pragma("unroll") for (int k = 0; k < 2; ++k) dst[n][k] = *(const PG8_LAS bf16x8*)(lds + PG8_SB(b, h) + boff + n * 2048 + k * 1024); } while (0)
; #define PG8_MMA(ai, bj, At, Bt) do { __builtin_amdgcn_s_setprio(1); _Pragma("unroll") for (int m = 0; m < 4; ++m) _Pragma("unroll") for (int n = 0; n < 2; ++n) _Pragma("unroll") for (int k = 0; k < 2; ++k) \
;         acc[ai][bj][m][n] = __builtin_amdgcn_mfma_f32_16x16x32_bf16(Bt[n][k], At[m][k], acc[ai][bj][m][n], 0, 0, 0); __builtin_amdgcn_s_setprio(0); } while (0)
; #define PG8_WAIT_V(n) asm volatile("s_waitcnt vmcnt(" #n ")" ::: "memory")
; #define PG8_WAIT_L(n) asm volatile("s_waitcnt lgkmcnt(" #n ")" ::: "memory")
; #define PG8_BAR __builtin_amdgcn_s_barrier()
; #define PG8_SCHED __builtin_amdgcn_sched_barrier(0)
; template <class Epi, class Sched, bool ALIGN_EPI = false, bool SP2 = false>
; __device__ __forceinline__ void gemm_phase(PG8_LAS unsigned char* lds, const Gemm g, const Sched& S, const Epi& E, int tid_in) {
;     ...
;             PG8_LDB(B0, 0, 0); PG8_LDB(B1, 0, 1); PG8_SCHED; PG8_LDA(At, 0, 0); PG8_STAGE(PG8_SA(1, 1), a1 + hstep, voffA);
;             PG8_WAIT_V(8); PG8_WAIT_L(0); PG8_BAR; PG8_MMA(0, 0, At, B0); PG8_MMA(0, 1, At, B1); PG8_BAR; PG8_SCHED;
;             PG8_LDA(At, 0, 1); PG8_STAGE(PG8_SB(0, 0), b2, voffB); PG8_STAGE(PG8_SB(0, 1), b2 + hstep, voffB); PG8_STAGE(PG8_SA(0, 0), a2, voffA);
.LBB0_1305:
	s_add_u32 s50, s48, 0xfffe0080
	s_addc_u32 s51, s49, -1
	s_add_i32 s64, 0, 0x10000
	s_cmp_eq_u32 s63, 4
	s_cselect_b32 s53, s0, s51
	s_cselect_b32 s52, s1, s50
	s_cselect_b32 s51, s39, s62
	s_cselect_b32 s50, s41, s61
	s_add_i32 s66, 0, 0x14000
	v_add_u32_e32 v142, s64, v172
	v_add_u32_e32 v168, s66, v172
	ds_read_b128 v[130:133], v142
	ds_read_b128 v[134:137], v142 offset:1024
	ds_read_b128 v[138:141], v142 offset:2048
	ds_read_b128 v[142:145], v142 offset:3072
	ds_read_b128 v[146:149], v168
	ds_read_b128 v[160:163], v168 offset:1024
	ds_read_b128 v[164:167], v168 offset:2048
	ds_read_b128 v[174:177], v168 offset:3072
	v_lshl_add_u64 v[168:169], s[48:49], 0, v[156:157]
	s_add_i32 m0, s16, 0xc000
	ds_read_b128 v[178:181], v173
	ds_read_b128 v[182:185], v173 offset:1024
	ds_read_b128 v[190:193], v173 offset:2048
	ds_read_b128 v[194:197], v173 offset:3072
	ds_read_b128 v[198:201], v173 offset:4096
	ds_read_b128 v[202:205], v173 offset:5120
	ds_read_b128 v[206:209], v173 offset:6144
	ds_read_b128 v[210:213], v173 offset:7168
	global_load_lds_dwordx4 v[168:169], off
	v_lshl_add_u64 v[168:169], s[48:49], 0, v[158:159]
	s_add_i32 m0, s16, 0xe000
	s_nop 0
	global_load_lds_dwordx4 v[168:169], off
	s_waitcnt vmcnt(8)
	s_waitcnt lgkmcnt(0)
	s_barrier
	s_setprio 1
	s_waitcnt lgkmcnt(0)
	v_mfma_f32_16x16x32_bf16 v[126:129], v[130:133], v[178:181], v[126:129]
	v_mfma_f32_16x16x32_bf16 v[122:125], v[138:141], v[178:181], v[122:125]
	v_mfma_f32_16x16x32_bf16 v[110:113], v[130:133], v[190:193], v[110:113]
	v_mfma_f32_16x16x32_bf16 v[106:109], v[138:141], v[190:193], v[106:109]
	v_mfma_f32_16x16x32_bf16 v[98:101], v[130:133], v[198:201], v[98:101]
	v_mfma_f32_16x16x32_bf16 v[90:93], v[138:141], v[198:201], v[90:93]
	v_mfma_f32_16x16x32_bf16 v[82:85], v[130:133], v[206:209], v[82:85]
	v_mfma_f32_16x16x32_bf16 v[72:75], v[138:141], v[206:209], v[72:75]
	v_mfma_f32_16x16x32_bf16 v[126:129], v[134:137], v[182:185], v[126:129]
	v_mfma_f32_16x16x32_bf16 v[122:125], v[142:145], v[182:185], v[122:125]
	v_mfma_f32_16x16x32_bf16 v[110:113], v[134:137], v[194:197], v[110:113]
	v_mfma_f32_16x16x32_bf16 v[106:109], v[142:145], v[194:197], v[106:109]
	v_mfma_f32_16x16x32_bf16 v[98:101], v[134:137], v[202:205], v[98:101]
	v_mfma_f32_16x16x32_bf16 v[90:93], v[142:145], v[202:205], v[90:93]
	v_mfma_f32_16x16x32_bf16 v[82:85], v[134:137], v[210:213], v[82:85]
	v_mfma_f32_16x16x32_bf16 v[72:75], v[142:145], v[210:213], v[72:75]
	v_mfma_f32_16x16x32_bf16 v[118:121], v[146:149], v[178:181], v[118:121]
	v_mfma_f32_16x16x32_bf16 v[114:117], v[164:167], v[178:181], v[114:117]
	v_mfma_f32_16x16x32_bf16 v[102:105], v[146:149], v[190:193], v[102:105]
	v_mfma_f32_16x16x32_bf16 v[94:97], v[164:167], v[190:193], v[94:97]
	v_mfma_f32_16x16x32_bf16 v[86:89], v[146:149], v[198:201], v[86:89]
	v_mfma_f32_16x16x32_bf16 v[76:79], v[164:167], v[198:201], v[76:79]
	v_mfma_f32_16x16x32_bf16 v[68:71], v[146:149], v[206:209], v[68:71]
	v_mfma_f32_16x16x32_bf16 v[64:67], v[164:167], v[206:209], v[64:67]
	v_mfma_f32_16x16x32_bf16 v[118:121], v[160:163], v[182:185], v[118:121]
	v_mfma_f32_16x16x32_bf16 v[114:117], v[174:177], v[182:185], v[114:117]
	v_mfma_f32_16x16x32_bf16 v[102:105], v[160:163], v[194:197], v[102:105]
	v_mfma_f32_16x16x32_bf16 v[94:97], v[174:177], v[194:197], v[94:97]
	v_mfma_f32_16x16x32_bf16 v[86:89], v[160:163], v[202:205], v[86:89]
	v_mfma_f32_16x16x32_bf16 v[76:79], v[174:177], v[202:205], v[76:79]
	v_mfma_f32_16x16x32_bf16 v[68:71], v[160:163], v[210:213], v[68:71]
	v_mfma_f32_16x16x32_bf16 v[64:67], v[174:177], v[210:213], v[64:67]
	s_setprio 0
	s_barrier
	s_add_i32 s64, s64, s15
	v_lshl_add_u64 v[168:169], s[50:51], 0, v[80:81]
	s_mov_b32 m0, s64
	ds_read_b128 v[178:181], v173 offset:16384
	ds_read_b128 v[182:185], v173 offset:17408
	ds_read_b128 v[190:193], v173 offset:18432
	ds_read_b128 v[194:197], v173 offset:19456
	ds_read_b128 v[198:201], v173 offset:20480
	ds_read_b128 v[202:205], v173 offset:21504
	ds_read_b128 v[206:209], v173 offset:22528
	ds_read_b128 v[210:213], v173 offset:23552
	global_load_lds_dwordx4 v[168:169], off
	s_add_i32 m0, s64, 0x2000
	s_add_u32 s64, s50, 0x20000
	v_lshl_add_u64 v[186:187], s[50:51], 0, v[154:155]
	s_addc_u32 s65, s51, 0
	s_add_i32 s66, s66, s15
	global_load_lds_dwordx4 v[186:187], off
	v_lshl_add_u64 v[188:189], s[64:65], 0, v[80:81]
	s_mov_b32 m0, s66
	v_lshl_add_u64 v[214:215], s[52:53], 0, v[152:153]
	global_load_lds_dwordx4 v[188:189], off
	v_lshl_add_u64 v[188:189], s[64:65], 0, v[154:155]
	s_add_i32 m0, s66, 0x2000
	s_nop 0
	global_load_lds_dwordx4 v[188:189], off
	v_lshl_add_u64 v[188:189], s[52:53], 0, v[150:151]
	s_mov_b32 m0, s16
	s_nop 0
	global_load_lds_dwordx4 v[188:189], off
	s_mov_b32 m0, s17
	s_nop 0
	global_load_lds_dwordx4 v[214:215], off
	s_waitcnt vmcnt(8)
	s_waitcnt lgkmcnt(0)
	s_barrier
; #define PG8_STAGE(bufoff, gbase, voff) do { _Pragma("unroll") for (int _i = 0; _i < 2; ++_i) \
;         __builtin_amdgcn_global_load_lds((const unsigned*)((const char*)(gbase) + (voff)[_i]), (PG8_LAS unsigned*)(lds + (bufoff) + ldsw + _i * 8192), 16, 0, 0); } while (0)
; #define PG8_LDA(dst, b, h) do { _Pragma("unroll") for (int m = 0; m < 4; ++m) _Pragma("unroll") for (int k = 0; k < 2; ++k) dst[m][k] = *(const PG8_LAS bf16x8*)(lds + PG8_SA(b, h) + aoff + m * 2048 + k * 1024); } while (0)
; #define PG8_LDB(dst, b, h) do { _Pragma("unroll") for (int n = 0; n < 2; ++n) _Pragma("unroll") for (int k = 0; k < 2; ++k) dst[n][k] = *(const PG8_LAS bf16x8*)(lds + PG8_SB(b, h) + boff + n * 2048 + k * 1024); } while (0)
; #define PG8_MMA(ai, bj, At, Bt) do { __builtin_amdgcn_s_setprio(1); _Pragma("unroll") for (int m = 0; m < 4; ++m) _Pragma("unroll") for (int n = 0; n < 2; ++n) _Pragma("unroll") for (int k = 0; k < 2; ++k) \
;         acc[ai][bj][m][n] = __builtin_amdgcn_mfma_f32_16x16x32_bf16(Bt[n][k], At[m][k], acc[ai][bj][m][n], 0, 0, 0); __builtin_amdgcn_s_setprio(0); } while (0)
; #define PG8_WAIT_V(n) asm volatile("s_waitcnt vmcnt(" #n ")" ::: "memory")
; #define PG8_WAIT_L(n) asm volatile("s_waitcnt lgkmcnt(" #n ")" ::: "memory")
; #define PG8_BAR __builtin_amdgcn_s_barrier()
; #define PG8_SCHED __builtin_amdgcn_sched_barrier(0)
; template <class Epi, class Sched, bool ALIGN_EPI = false, bool SP2 = false>
; __device__ __forceinline__ void gemm_phase(PG8_LAS unsigned char* lds, const Gemm g, const Sched& S, const Epi& E, int tid_in) {
;     ...
;             PG8_WAIT_V(8); PG8_WAIT_L(0); PG8_BAR; PG8_MMA(1, 0, At, B0); PG8_MMA(1, 1, At, B1); PG8_BAR; PG8_SCHED;
;             PG8_LDB(B0, 1, 0); PG8_LDB(B1, 1, 1); PG8_SCHED; PG8_LDA(At, 1, 0); PG8_STAGE(PG8_SA(0, 1), a2 + hstep, voffA);
;             PG8_WAIT_V(8); PG8_WAIT_L(0); PG8_BAR; PG8_MMA(0, 0, At, B0); PG8_MMA(0, 1, At, B1); PG8_BAR; PG8_SCHED;
	s_setprio 1
	s_waitcnt lgkmcnt(0)
	v_mfma_f32_16x16x32_bf16 v[60:63], v[130:133], v[178:181], v[60:63]
	v_mfma_f32_16x16x32_bf16 v[56:59], v[138:141], v[178:181], v[56:59]
	v_mfma_f32_16x16x32_bf16 v[48:51], v[130:133], v[190:193], v[48:51]
	v_mfma_f32_16x16x32_bf16 v[40:43], v[138:141], v[190:193], v[40:43]
	v_mfma_f32_16x16x32_bf16 v[32:35], v[130:133], v[198:201], v[32:35]
	v_mfma_f32_16x16x32_bf16 v[24:27], v[138:141], v[198:201], v[24:27]
	v_mfma_f32_16x16x32_bf16 v[16:19], v[130:133], v[206:209], v[16:19]
	v_mfma_f32_16x16x32_bf16 v[8:11], v[138:141], v[206:209], v[8:11]
	v_mfma_f32_16x16x32_bf16 v[60:63], v[134:137], v[182:185], v[60:63]
	v_mfma_f32_16x16x32_bf16 v[56:59], v[142:145], v[182:185], v[56:59]
	v_mfma_f32_16x16x32_bf16 v[48:51], v[134:137], v[194:197], v[48:51]
	v_mfma_f32_16x16x32_bf16 v[40:43], v[142:145], v[194:197], v[40:43]
	v_mfma_f32_16x16x32_bf16 v[32:35], v[134:137], v[202:205], v[32:35]
	v_mfma_f32_16x16x32_bf16 v[24:27], v[142:145], v[202:205], v[24:27]
	v_mfma_f32_16x16x32_bf16 v[16:19], v[134:137], v[210:213], v[16:19]
	v_mfma_f32_16x16x32_bf16 v[8:11], v[142:145], v[210:213], v[8:11]
	v_mfma_f32_16x16x32_bf16 v[52:55], v[146:149], v[178:181], v[52:55]
	v_mfma_f32_16x16x32_bf16 v[44:47], v[164:167], v[178:181], v[44:47]
	v_mfma_f32_16x16x32_bf16 v[36:39], v[146:149], v[190:193], v[36:39]
	v_mfma_f32_16x16x32_bf16 v[28:31], v[164:167], v[190:193], v[28:31]
	v_mfma_f32_16x16x32_bf16 v[20:23], v[146:149], v[198:201], v[20:23]
	v_mfma_f32_16x16x32_bf16 v[12:15], v[164:167], v[198:201], v[12:15]
	v_mfma_f32_16x16x32_bf16 v[4:7], v[146:149], v[206:209], v[4:7]
	v_mfma_f32_16x16x32_bf16 v[0:3], v[164:167], v[206:209], v[0:3]
	v_mfma_f32_16x16x32_bf16 v[52:55], v[160:163], v[182:185], v[52:55]
	v_mfma_f32_16x16x32_bf16 v[44:47], v[174:177], v[182:185], v[44:47]
	v_mfma_f32_16x16x32_bf16 v[36:39], v[160:163], v[194:197], v[36:39]
	v_mfma_f32_16x16x32_bf16 v[28:31], v[174:177], v[194:197], v[28:31]
	v_mfma_f32_16x16x32_bf16 v[20:23], v[160:163], v[202:205], v[20:23]
	v_mfma_f32_16x16x32_bf16 v[12:15], v[174:177], v[202:205], v[12:15]
	v_mfma_f32_16x16x32_bf16 v[4:7], v[160:163], v[210:213], v[4:7]
	v_mfma_f32_16x16x32_bf16 v[0:3], v[174:177], v[210:213], v[0:3]
	s_setprio 0
	s_barrier
	s_add_i32 s64, 0, 0x18000
	s_add_i32 s65, 0, 0x1c000
	v_add_u32_e32 v142, s64, v172
	v_add_u32_e32 v174, s65, v172
	ds_read_b128 v[130:133], v142
	ds_read_b128 v[134:137], v142 offset:1024
	ds_read_b128 v[138:141], v142 offset:2048
	ds_read_b128 v[142:145], v142 offset:3072
	ds_read_b128 v[146:149], v174
	ds_read_b128 v[160:163], v174 offset:1024
	ds_read_b128 v[164:167], v174 offset:2048
	ds_read_b128 v[174:177], v174 offset:3072
	s_add_u32 s52, s52, 0x20000
	s_addc_u32 s53, s53, 0
	s_mov_b32 m0, s18
	v_lshl_add_u64 v[226:227], s[52:53], 0, v[150:151]
	ds_read_b128 v[178:181], v173 offset:32768
	ds_read_b128 v[182:185], v173 offset:33792
	ds_read_b128 v[190:193], v173 offset:34816
	ds_read_b128 v[194:197], v173 offset:35840
	ds_read_b128 v[198:201], v173 offset:36864
	ds_read_b128 v[202:205], v173 offset:37888
	ds_read_b128 v[206:209], v173 offset:38912
	ds_read_b128 v[210:213], v173 offset:39936
	global_load_lds_dwordx4 v[226:227], off
	v_lshl_add_u64 v[226:227], s[52:53], 0, v[152:153]
	s_mov_b32 m0, s19
	s_nop 0
	global_load_lds_dwordx4 v[226:227], off
	s_waitcnt vmcnt(8)
	s_waitcnt lgkmcnt(0)
	s_barrier
	s_setprio 1
	s_waitcnt lgkmcnt(0)
	v_mfma_f32_16x16x32_bf16 v[126:129], v[130:133], v[178:181], v[126:129]
	v_mfma_f32_16x16x32_bf16 v[122:125], v[138:141], v[178:181], v[122:125]
	v_mfma_f32_16x16x32_bf16 v[110:113], v[130:133], v[190:193], v[110:113]
	v_mfma_f32_16x16x32_bf16 v[106:109], v[138:141], v[190:193], v[106:109]
	v_mfma_f32_16x16x32_bf16 v[98:101], v[130:133], v[198:201], v[98:101]
	v_mfma_f32_16x16x32_bf16 v[90:93], v[138:141], v[198:201], v[90:93]
	v_mfma_f32_16x16x32_bf16 v[82:85], v[130:133], v[206:209], v[82:85]
	v_mfma_f32_16x16x32_bf16 v[72:75], v[138:141], v[206:209], v[72:75]
	v_mfma_f32_16x16x32_bf16 v[126:129], v[134:137], v[182:185], v[126:129]
	v_mfma_f32_16x16x32_bf16 v[122:125], v[142:145], v[182:185], v[122:125]
	v_mfma_f32_16x16x32_bf16 v[110:113], v[134:137], v[194:197], v[110:113]
	v_mfma_f32_16x16x32_bf16 v[106:109], v[142:145], v[194:197], v[106:109]
	v_mfma_f32_16x16x32_bf16 v[98:101], v[134:137], v[202:205], v[98:101]
	v_mfma_f32_16x16x32_bf16 v[90:93], v[142:145], v[202:205], v[90:93]
	v_mfma_f32_16x16x32_bf16 v[82:85], v[134:137], v[210:213], v[82:85]
	v_mfma_f32_16x16x32_bf16 v[72:75], v[142:145], v[210:213], v[72:75]
	v_mfma_f32_16x16x32_bf16 v[118:121], v[146:149], v[178:181], v[118:121]
	v_mfma_f32_16x16x32_bf16 v[114:117], v[164:167], v[178:181], v[114:117]
	v_mfma_f32_16x16x32_bf16 v[102:105], v[146:149], v[190:193], v[102:105]
	v_mfma_f32_16x16x32_bf16 v[94:97], v[164:167], v[190:193], v[94:97]
	v_mfma_f32_16x16x32_bf16 v[86:89], v[146:149], v[198:201], v[86:89]
	v_mfma_f32_16x16x32_bf16 v[76:79], v[164:167], v[198:201], v[76:79]
	v_mfma_f32_16x16x32_bf16 v[68:71], v[146:149], v[206:209], v[68:71]
	v_mfma_f32_16x16x32_bf16 v[64:67], v[164:167], v[206:209], v[64:67]
	v_mfma_f32_16x16x32_bf16 v[118:121], v[160:163], v[182:185], v[118:121]
	v_mfma_f32_16x16x32_bf16 v[114:117], v[174:177], v[182:185], v[114:117]
	v_mfma_f32_16x16x32_bf16 v[102:105], v[160:163], v[194:197], v[102:105]
	v_mfma_f32_16x16x32_bf16 v[94:97], v[174:177], v[194:197], v[94:97]
	v_mfma_f32_16x16x32_bf16 v[86:89], v[160:163], v[202:205], v[86:89]
	v_mfma_f32_16x16x32_bf16 v[76:79], v[174:177], v[202:205], v[76:79]
	v_mfma_f32_16x16x32_bf16 v[68:71], v[160:163], v[210:213], v[68:71]
	v_mfma_f32_16x16x32_bf16 v[64:67], v[174:177], v[210:213], v[64:67]
	s_setprio 0
	s_barrier
; #define PG8_STAGE(bufoff, gbase, voff) do { _Pragma("unroll") for (int _i = 0; _i < 2; ++_i) \
;         __builtin_amdgcn_global_load_lds((const unsigned*)((const char*)(gbase) + (voff)[_i]), (PG8_LAS unsigned*)(lds + (bufoff) + ldsw + _i * 8192), 16, 0, 0); } while (0)
; #define PG8_LDA(dst, b, h) do { _Pragma("unroll") for (int m = 0; m < 4; ++m) _Pragma("unroll") for (int k = 0; k < 2; ++k) dst[m][k] = *(const PG8_LAS bf16x8*)(lds + PG8_SA(b, h) + aoff + m * 2048 + k * 1024); } while (0)
; #define PG8_MMA(ai, bj, At, Bt) do { __builtin_amdgcn_s_setprio(1); _Pragma("unroll") for (int m = 0; m < 4; ++m) _Pragma("unroll") for (int n = 0; n < 2; ++n) _Pragma("unroll") for (int k = 0; k < 2; ++k) \
;         acc[ai][bj][m][n] = __builtin_amdgcn_mfma_f32_16x16x32_bf16(Bt[n][k], At[m][k], acc[ai][bj][m][n], 0, 0, 0); __builtin_amdgcn_s_setprio(0); } while (0)
; #define PG8_WAIT_V(n) asm volatile("s_waitcnt vmcnt(" #n ")" ::: "memory")
; #define PG8_WAIT_L(n) asm volatile("s_waitcnt lgkmcnt(" #n ")" ::: "memory")
; #define PG8_BAR __builtin_amdgcn_s_barrier()
; #define PG8_SCHED __builtin_amdgcn_sched_barrier(0)
; template <class Epi, class Sched, bool ALIGN_EPI = false, bool SP2 = false>
; __device__ __forceinline__ void gemm_phase(PG8_LAS unsigned char* lds, const Gemm g, const Sched& S, const Epi& E, int tid_in) {
;     ...
;             PG8_LDA(At, 1, 1); PG8_STAGE(PG8_SB(1, 0), b3, voffB); PG8_STAGE(PG8_SB(1, 1), b3 + hstep, voffB); PG8_STAGE(PG8_SA(1, 0), a3, voffA);
;             PG8_WAIT_V(8); PG8_WAIT_L(0); PG8_BAR; PG8_MMA(1, 0, At, B0); PG8_MMA(1, 1, At, B1); PG8_BAR; PG8_SCHED;
;     __device__ __forceinline__ void operator()(const pg8::f32x4 (&acc)[2][2][4][2], const pg8::Unit& u, int wr, int wc, int fr, int fq) const {
;     ...
;             u32x4 sv[4][2], av[4][2];
;             const size_t off0 = (size_t)(u.pm * 256 + ai * 128 + wr * 64 + fr) * 1024 + u.pn * 256 + wc * 32 + 8 * fq;
; #pragma unroll
;             for (int m = 0; m < 4; ++m)
; #pragma unroll
;                 for (int bj = 0; bj < 2; ++bj) { sv[m][bj] = *(const u32x4*)(S + off0 + (size_t)m * 16 * 1024 + bj * 128); if (ADD) av[m][bj] = *(const u32x4*)(A + off0 + (size_t)m * 16 * 1024 + bj * 128); }
	s_add_i32 s52, s64, s15
	v_lshl_add_u64 v[168:169], v[168:169], 0, s[6:7]
	s_mov_b32 m0, s52
	ds_read_b128 v[178:181], v173 offset:49152
	ds_read_b128 v[182:185], v173 offset:50176
	ds_read_b128 v[190:193], v173 offset:51200
	ds_read_b128 v[194:197], v173 offset:52224
	ds_read_b128 v[198:201], v173 offset:53248
	ds_read_b128 v[202:205], v173 offset:54272
	ds_read_b128 v[206:209], v173 offset:55296
	ds_read_b128 v[210:213], v173 offset:56320
	global_load_lds_dwordx4 v[168:169], off
	s_add_i32 m0, s52, 0x2000
	s_add_u32 s50, s50, 0x20080
	v_lshl_add_u64 v[168:169], v[186:187], 0, s[6:7]
	s_addc_u32 s51, s51, 0
	s_add_i32 s52, s65, s15
	global_load_lds_dwordx4 v[168:169], off
	v_lshl_add_u64 v[168:169], s[50:51], 0, v[80:81]
	s_mov_b32 m0, s52
	s_nop 0
	global_load_lds_dwordx4 v[168:169], off
	v_lshl_add_u64 v[168:169], s[50:51], 0, v[154:155]
	s_add_i32 m0, s52, 0x2000
	s_nop 0
	global_load_lds_dwordx4 v[168:169], off
	v_lshl_add_u64 v[168:169], v[188:189], 0, s[6:7]
	s_mov_b32 m0, s54
	s_nop 0
	global_load_lds_dwordx4 v[168:169], off
	v_lshl_add_u64 v[168:169], v[214:215], 0, s[6:7]
	s_mov_b32 m0, s55
	s_nop 0
	global_load_lds_dwordx4 v[168:169], off
	s_waitcnt vmcnt(8)
	s_waitcnt lgkmcnt(0)
	s_barrier
	s_setprio 1
	s_waitcnt lgkmcnt(0)
	v_mfma_f32_16x16x32_bf16 v[60:63], v[130:133], v[178:181], v[60:63]
	v_mfma_f32_16x16x32_bf16 v[56:59], v[138:141], v[178:181], v[56:59]
	v_mfma_f32_16x16x32_bf16 v[48:51], v[130:133], v[190:193], v[48:51]
	v_mfma_f32_16x16x32_bf16 v[40:43], v[138:141], v[190:193], v[40:43]
	v_mfma_f32_16x16x32_bf16 v[32:35], v[130:133], v[198:201], v[32:35]
	v_mfma_f32_16x16x32_bf16 v[24:27], v[138:141], v[198:201], v[24:27]
	v_mfma_f32_16x16x32_bf16 v[16:19], v[130:133], v[206:209], v[16:19]
	v_mfma_f32_16x16x32_bf16 v[8:11], v[138:141], v[206:209], v[8:11]
	v_mfma_f32_16x16x32_bf16 v[60:63], v[134:137], v[182:185], v[60:63]
	v_mfma_f32_16x16x32_bf16 v[56:59], v[142:145], v[182:185], v[56:59]
	v_mfma_f32_16x16x32_bf16 v[48:51], v[134:137], v[194:197], v[48:51]
	v_mfma_f32_16x16x32_bf16 v[40:43], v[142:145], v[194:197], v[40:43]
	v_mfma_f32_16x16x32_bf16 v[32:35], v[134:137], v[202:205], v[32:35]
	v_mfma_f32_16x16x32_bf16 v[24:27], v[142:145], v[202:205], v[24:27]
	v_mfma_f32_16x16x32_bf16 v[16:19], v[134:137], v[210:213], v[16:19]
	v_mfma_f32_16x16x32_bf16 v[8:11], v[142:145], v[210:213], v[8:11]
	v_mfma_f32_16x16x32_bf16 v[52:55], v[146:149], v[178:181], v[52:55]
	v_mfma_f32_16x16x32_bf16 v[44:47], v[164:167], v[178:181], v[44:47]
	v_mfma_f32_16x16x32_bf16 v[36:39], v[146:149], v[190:193], v[36:39]
	v_mfma_f32_16x16x32_bf16 v[28:31], v[164:167], v[190:193], v[28:31]
	v_mfma_f32_16x16x32_bf16 v[20:23], v[146:149], v[198:201], v[20:23]
	v_mfma_f32_16x16x32_bf16 v[12:15], v[164:167], v[198:201], v[12:15]
	v_mfma_f32_16x16x32_bf16 v[4:7], v[146:149], v[206:209], v[4:7]
	v_mfma_f32_16x16x32_bf16 v[0:3], v[164:167], v[206:209], v[0:3]
	v_mfma_f32_16x16x32_bf16 v[52:55], v[160:163], v[182:185], v[52:55]
	v_mfma_f32_16x16x32_bf16 v[44:47], v[174:177], v[182:185], v[44:47]
	v_mfma_f32_16x16x32_bf16 v[36:39], v[160:163], v[194:197], v[36:39]
	v_mfma_f32_16x16x32_bf16 v[28:31], v[174:177], v[194:197], v[28:31]
	v_mfma_f32_16x16x32_bf16 v[20:23], v[160:163], v[202:205], v[20:23]
	v_mfma_f32_16x16x32_bf16 v[12:15], v[174:177], v[202:205], v[12:15]
	v_mfma_f32_16x16x32_bf16 v[4:7], v[160:163], v[210:213], v[4:7]
	v_mfma_f32_16x16x32_bf16 v[0:3], v[174:177], v[210:213], v[0:3]
	s_setprio 0
	s_barrier
	s_add_i32 s63, s63, 2
	s_add_u32 s48, s48, 0x100
	s_addc_u32 s49, s49, 0
	s_add_u32 s61, s61, 0x100
	s_addc_u32 s62, s62, 0
	s_cmp_gt_u32 s63, 5
	s_cbranch_scc0 .LBB0_1305
	s_lshl_b32 s0, s46, 8
	v_mov_b32_e32 v130, v170
	v_mov_b32_e32 v131, v171
	s_add_i32 s0, s0, s47
	s_nop 0
	v_add_u32_e32 v160, s0, v130
	s_lshl_b32 s0, s60, 8
	s_ashr_i32 s1, s0, 31
	s_lshl_b64 s[0:1], s[0:1], 1
	v_lshlrev_b32_e32 v130, 3, v131
	s_add_u32 s0, s56, s0
	v_ashrrev_i32_e32 v131, 31, v130
	v_ashrrev_i32_e32 v161, 31, v160
	s_addc_u32 s1, s57, s1
	v_lshl_add_u64 v[162:163], v[130:131], 1, s[0:1]
	v_lshlrev_b64 v[130:131], 11, v[160:161]
	v_lshl_add_u64 v[186:187], v[162:163], 0, v[130:131]
	global_load_dwordx4 v[174:177], v[186:187], off
	global_load_dwordx4 v[178:181], v[186:187], off offset:256
	v_add_co_u32_e32 v168, vcc, s11, v186
	s_mov_b64 s[0:1], -1
	s_nop 0
	v_addc_co_u32_e32 v169, vcc, 0, v187, vcc
	global_load_dwordx4 v[182:185], v[168:169], off
	global_load_dwordx4 v[146:149], v[168:169], off offset:256
	v_add_co_u32_e32 v166, vcc, s33, v186
	s_nop 0
	v_addc_co_u32_e32 v167, vcc, 0, v187, vcc
	global_load_dwordx4 v[142:145], v[166:167], off
	global_load_dwordx4 v[138:141], v[166:167], off offset:256
	v_add_co_u32_e32 v164, vcc, s10, v186
	s_nop 0
	v_addc_co_u32_e32 v165, vcc, 0, v187, vcc
	global_load_dwordx4 v[134:137], v[164:165], off
	global_load_dwordx4 v[130:133], v[164:165], off offset:256
	s_and_b64 vcc, exec, s[8:9]
	s_cbranch_vccz .LBB0_1308
	s_barrier
; __device__ __forceinline__ float bflo(unsigned w) { return __uint_as_float(w << 16); }
; __device__ __forceinline__ float bfhi(unsigned w) { return __uint_as_float(w & 0xffff0000u); }
; __device__ __forceinline__ u32x4 pack8(f32x4 a, f32x4 b) { u32x4 w; w.x = cvtpk(a[0], a[1]); w.y = cvtpk(a[2], a[3]); w.z = cvtpk(b[0], b[1]); w.w = cvtpk(b[2], b[3]); return w; }
;     __device__ __forceinline__ void operator()(const pg8::f32x4 (&acc)[2][2][4][2], const pg8::Unit& u, int wr, int wc, int fr, int fq) const {
;     ...
;             u32x4 sv[4][2], av[4][2];
;             const size_t off0 = (size_t)(u.pm * 256 + ai * 128 + wr * 64 + fr) * 1024 + u.pn * 256 + wc * 32 + 8 * fq;
; #pragma unroll
;             for (int m = 0; m < 4; ++m)
; #pragma unroll
;                 for (int bj = 0; bj < 2; ++bj) { sv[m][bj] = *(const u32x4*)(S + off0 + (size_t)m * 16 * 1024 + bj * 128); if (ADD) av[m][bj] = *(const u32x4*)(A + off0 + (size_t)m * 16 * 1024 + bj * 128); }
; #pragma unroll
;             for (int m = 0; m < 4; ++m)
; #pragma unroll
;                 for (int bj = 0; bj < 2; ++bj) {
;                     const u32x4 s = sv[m][bj];
;                     f32x4 v0 = acc[ai][bj][m][0], v1 = acc[ai][bj][m][1];
;                     v0[0] *= bflo(s.x); v0[1] *= bfhi(s.x); v0[2] *= bflo(s.y); v0[3] *= bfhi(s.y); v1[0] *= bflo(s.z); v1[1] *= bfhi(s.z); v1[2] *= bflo(s.w); v1[3] *= bfhi(s.w);
;                     if (ADD) { const u32x4 a = av[m][bj];
;                         v0[0] += bflo(a.x); v0[1] += bfhi(a.x); v0[2] += bflo(a.y); v0[3] += bfhi(a.y); v1[0] += bflo(a.z); v1[1] += bfhi(a.z); v1[2] += bflo(a.w); v1[3] += bfhi(a.w); }
;                     *(u32x4*)(S + off0 + (size_t)m * 16 * 1024 + bj * 128) = pack8(v0, v1);
;                 }
.LBB0_1308:
	s_waitcnt vmcnt(4)
	v_lshlrev_b32_e32 v188, 16, v174
	v_and_b32_e32 v189, 0xffff0000, v174
	v_lshlrev_b32_e32 v174, 16, v175
	v_and_b32_e32 v175, 0xffff0000, v175
	v_pk_mul_f32 v[128:129], v[128:129], v[174:175]
	v_lshlrev_b32_e32 v174, 16, v176
	v_and_b32_e32 v175, 0xffff0000, v176
	v_pk_mul_f32 v[174:175], v[122:123], v[174:175]
	v_lshlrev_b32_e32 v122, 16, v177
	v_and_b32_e32 v123, 0xffff0000, v177
	v_pk_mul_f32 v[126:127], v[126:127], v[188:189]
	v_pk_mul_f32 v[176:177], v[124:125], v[122:123]
	v_cvt_pk_bf16_f32 v122, v126, v127
	v_cvt_pk_bf16_f32 v123, v128, v129
	v_cvt_pk_bf16_f32 v124, v174, v175
	v_cvt_pk_bf16_f32 v125, v176, v177
	global_store_dwordx4 v[186:187], v[122:125], off
	s_nop 1
	v_lshlrev_b32_e32 v122, 16, v178
	v_and_b32_e32 v123, 0xffff0000, v178
	v_pk_mul_f32 v[118:119], v[118:119], v[122:123]
	v_lshlrev_b32_e32 v122, 16, v179
	v_and_b32_e32 v123, 0xffff0000, v179
	v_pk_mul_f32 v[120:121], v[120:121], v[122:123]
	v_lshlrev_b32_e32 v122, 16, v180
	v_and_b32_e32 v123, 0xffff0000, v180
	v_pk_mul_f32 v[122:123], v[114:115], v[122:123]
	v_lshlrev_b32_e32 v114, 16, v181
	v_and_b32_e32 v115, 0xffff0000, v181
	v_pk_mul_f32 v[124:125], v[116:117], v[114:115]
	v_cvt_pk_bf16_f32 v114, v118, v119
	v_cvt_pk_bf16_f32 v115, v120, v121
	v_cvt_pk_bf16_f32 v116, v122, v123
	v_cvt_pk_bf16_f32 v117, v124, v125
	global_store_dwordx4 v[186:187], v[114:117], off offset:256
	s_nop 1
	v_lshlrev_b32_e32 v114, 16, v182
	v_and_b32_e32 v115, 0xffff0000, v182
	v_pk_mul_f32 v[110:111], v[110:111], v[114:115]
	v_lshlrev_b32_e32 v114, 16, v183
	v_and_b32_e32 v115, 0xffff0000, v183
	v_pk_mul_f32 v[112:113], v[112:113], v[114:115]
	v_lshlrev_b32_e32 v114, 16, v184
	v_and_b32_e32 v115, 0xffff0000, v184
	v_pk_mul_f32 v[114:115], v[106:107], v[114:115]
	v_lshlrev_b32_e32 v106, 16, v185
	v_and_b32_e32 v107, 0xffff0000, v185
	v_pk_mul_f32 v[116:117], v[108:109], v[106:107]
	v_cvt_pk_bf16_f32 v106, v110, v111
	v_cvt_pk_bf16_f32 v107, v112, v113
	v_cvt_pk_bf16_f32 v108, v114, v115
	v_cvt_pk_bf16_f32 v109, v116, v117
	global_store_dwordx4 v[168:169], v[106:109], off
	s_nop 1
	v_lshlrev_b32_e32 v106, 16, v146
	v_and_b32_e32 v107, 0xffff0000, v146
	v_pk_mul_f32 v[102:103], v[102:103], v[106:107]
	v_lshlrev_b32_e32 v106, 16, v147
	v_and_b32_e32 v107, 0xffff0000, v147
	v_pk_mul_f32 v[104:105], v[104:105], v[106:107]
	v_lshlrev_b32_e32 v106, 16, v148
	v_and_b32_e32 v107, 0xffff0000, v148
	v_pk_mul_f32 v[106:107], v[94:95], v[106:107]
	v_lshlrev_b32_e32 v94, 16, v149
	v_and_b32_e32 v95, 0xffff0000, v149
	v_pk_mul_f32 v[108:109], v[96:97], v[94:95]
	v_cvt_pk_bf16_f32 v94, v102, v103
	v_cvt_pk_bf16_f32 v95, v104, v105
	v_cvt_pk_bf16_f32 v96, v106, v107
	v_cvt_pk_bf16_f32 v97, v108, v109
	global_store_dwordx4 v[168:169], v[94:97], off offset:256
	s_waitcnt vmcnt(7)
	s_nop 0
	v_lshlrev_b32_e32 v94, 16, v142
	v_and_b32_e32 v95, 0xffff0000, v142
	v_pk_mul_f32 v[94:95], v[98:99], v[94:95]
	v_lshlrev_b32_e32 v98, 16, v144
	v_and_b32_e32 v99, 0xffff0000, v144
	v_lshlrev_b32_e32 v96, 16, v143
	v_and_b32_e32 v97, 0xffff0000, v143
	v_pk_mul_f32 v[98:99], v[90:91], v[98:99]
	v_lshlrev_b32_e32 v90, 16, v145
	v_and_b32_e32 v91, 0xffff0000, v145
	v_pk_mul_f32 v[96:97], v[100:101], v[96:97]
	v_pk_mul_f32 v[100:101], v[92:93], v[90:91]
	v_cvt_pk_bf16_f32 v90, v94, v95
	v_cvt_pk_bf16_f32 v91, v96, v97
	v_cvt_pk_bf16_f32 v92, v98, v99
	v_cvt_pk_bf16_f32 v93, v100, v101
	global_store_dwordx4 v[166:167], v[90:93], off
	s_waitcnt vmcnt(7)
	s_nop 0
	v_lshlrev_b32_e32 v90, 16, v138
	v_and_b32_e32 v91, 0xffff0000, v138
	v_pk_mul_f32 v[86:87], v[86:87], v[90:91]
	v_lshlrev_b32_e32 v90, 16, v139
	v_and_b32_e32 v91, 0xffff0000, v139
	v_pk_mul_f32 v[88:89], v[88:89], v[90:91]
	v_lshlrev_b32_e32 v90, 16, v140
	v_and_b32_e32 v91, 0xffff0000, v140
	v_pk_mul_f32 v[90:91], v[76:77], v[90:91]
	v_lshlrev_b32_e32 v76, 16, v141
	v_and_b32_e32 v77, 0xffff0000, v141
	v_pk_mul_f32 v[92:93], v[78:79], v[76:77]
	v_cvt_pk_bf16_f32 v76, v86, v87
	v_cvt_pk_bf16_f32 v77, v88, v89
	v_cvt_pk_bf16_f32 v78, v90, v91
	v_cvt_pk_bf16_f32 v79, v92, v93
	global_store_dwordx4 v[166:167], v[76:79], off offset:256
	s_waitcnt vmcnt(7)
	s_nop 0
	v_lshlrev_b32_e32 v76, 16, v134
	v_and_b32_e32 v77, 0xffff0000, v134
	v_pk_mul_f32 v[76:77], v[82:83], v[76:77]
	v_lshlrev_b32_e32 v82, 16, v136
	v_and_b32_e32 v83, 0xffff0000, v136
	v_lshlrev_b32_e32 v78, 16, v135
	v_and_b32_e32 v79, 0xffff0000, v135
	v_pk_mul_f32 v[82:83], v[72:73], v[82:83]
	v_lshlrev_b32_e32 v72, 16, v137
	v_and_b32_e32 v73, 0xffff0000, v137
	v_pk_mul_f32 v[78:79], v[84:85], v[78:79]
	v_pk_mul_f32 v[84:85], v[74:75], v[72:73]
	v_cvt_pk_bf16_f32 v72, v76, v77
	v_cvt_pk_bf16_f32 v73, v78, v79
	v_cvt_pk_bf16_f32 v74, v82, v83
	v_cvt_pk_bf16_f32 v75, v84, v85
	global_store_dwordx4 v[164:165], v[72:75], off
	s_waitcnt vmcnt(7)
	s_nop 0
	v_lshlrev_b32_e32 v72, 16, v130
	v_and_b32_e32 v73, 0xffff0000, v130
	v_pk_mul_f32 v[68:69], v[68:69], v[72:73]
	v_lshlrev_b32_e32 v72, 16, v131
	v_and_b32_e32 v73, 0xffff0000, v131
	v_pk_mul_f32 v[70:71], v[70:71], v[72:73]
	v_lshlrev_b32_e32 v72, 16, v132
	v_and_b32_e32 v73, 0xffff0000, v132
	v_pk_mul_f32 v[72:73], v[64:65], v[72:73]
	v_lshlrev_b32_e32 v64, 16, v133
	v_and_b32_e32 v65, 0xffff0000, v133
	v_pk_mul_f32 v[74:75], v[66:67], v[64:65]
	v_cvt_pk_bf16_f32 v64, v68, v69
	v_cvt_pk_bf16_f32 v65, v70, v71
	v_cvt_pk_bf16_f32 v66, v72, v73
	v_cvt_pk_bf16_f32 v67, v74, v75
	global_store_dwordx4 v[164:165], v[64:67], off offset:256
	s_nop 1
	v_add_u32_e32 v64, 0x80, v160
	v_ashrrev_i32_e32 v65, 31, v64
	v_lshlrev_b64 v[64:65], 11, v[64:65]
	v_lshl_add_u64 v[78:79], v[162:163], 0, v[64:65]
	global_load_dwordx4 v[66:69], v[78:79], off
	global_load_dwordx4 v[70:73], v[78:79], off offset:256
	v_add_co_u32_e32 v102, vcc, s11, v78
	s_nop 0
	v_addc_co_u32_e32 v103, vcc, 0, v79, vcc
	global_load_dwordx4 v[74:77], v[102:103], off
	global_load_dwordx4 v[82:85], v[102:103], off offset:256
	v_add_co_u32_e32 v104, vcc, s33, v78
	s_nop 0
	v_addc_co_u32_e32 v105, vcc, 0, v79, vcc
	global_load_dwordx4 v[86:89], v[104:105], off
	global_load_dwordx4 v[90:93], v[104:105], off offset:256
	v_add_co_u32_e32 v64, vcc, s10, v78
	s_nop 0
	v_addc_co_u32_e32 v65, vcc, 0, v79, vcc
	global_load_dwordx4 v[94:97], v[64:65], off
	global_load_dwordx4 v[98:101], v[64:65], off offset:256
	s_waitcnt vmcnt(7)
; __device__ __forceinline__ float bflo(unsigned w) { return __uint_as_float(w << 16); }
; __device__ __forceinline__ float bfhi(unsigned w) { return __uint_as_float(w & 0xffff0000u); }
; __device__ __forceinline__ u32x4 pack8(f32x4 a, f32x4 b) { u32x4 w; w.x = cvtpk(a[0], a[1]); w.y = cvtpk(a[2], a[3]); w.z = cvtpk(b[0], b[1]); w.w = cvtpk(b[2], b[3]); return w; }
;     __device__ __forceinline__ void operator()(const pg8::f32x4 (&acc)[2][2][4][2], const pg8::Unit& u, int wr, int wc, int fr, int fq) const {
;     ...
;             for (int m = 0; m < 4; ++m)
; #pragma unroll
;                 for (int bj = 0; bj < 2; ++bj) {
;                     const u32x4 s = sv[m][bj];
;                     f32x4 v0 = acc[ai][bj][m][0], v1 = acc[ai][bj][m][1];
;                     v0[0] *= bflo(s.x); v0[1] *= bfhi(s.x); v0[2] *= bflo(s.y); v0[3] *= bfhi(s.y); v1[0] *= bflo(s.z); v1[1] *= bfhi(s.z); v1[2] *= bflo(s.w); v1[3] *= bfhi(s.w);
;                     if (ADD) { const u32x4 a = av[m][bj];
;                         v0[0] += bflo(a.x); v0[1] += bfhi(a.x); v0[2] += bflo(a.y); v0[3] += bfhi(a.y); v1[0] += bflo(a.z); v1[1] += bfhi(a.z); v1[2] += bflo(a.w); v1[3] += bfhi(a.w); }
;                     *(u32x4*)(S + off0 + (size_t)m * 16 * 1024 + bj * 128) = pack8(v0, v1);
;                 }
	v_lshlrev_b32_e32 v106, 16, v66
	v_and_b32_e32 v107, 0xffff0000, v66
	v_lshlrev_b32_e32 v66, 16, v67
	v_and_b32_e32 v67, 0xffff0000, v67
	v_pk_mul_f32 v[62:63], v[62:63], v[66:67]
	v_lshlrev_b32_e32 v66, 16, v68
	v_and_b32_e32 v67, 0xffff0000, v68
	v_pk_mul_f32 v[66:67], v[56:57], v[66:67]
	v_lshlrev_b32_e32 v56, 16, v69
	v_and_b32_e32 v57, 0xffff0000, v69
	v_pk_mul_f32 v[60:61], v[60:61], v[106:107]
	v_pk_mul_f32 v[68:69], v[58:59], v[56:57]
	v_cvt_pk_bf16_f32 v56, v60, v61
	v_cvt_pk_bf16_f32 v57, v62, v63
	v_cvt_pk_bf16_f32 v58, v66, v67
	v_cvt_pk_bf16_f32 v59, v68, v69
	global_store_dwordx4 v[78:79], v[56:59], off
	s_andn2_b64 vcc, exec, s[36:37]
	s_waitcnt vmcnt(7)
	v_lshlrev_b32_e32 v56, 16, v70
	v_and_b32_e32 v57, 0xffff0000, v70
	v_pk_mul_f32 v[52:53], v[52:53], v[56:57]
	v_lshlrev_b32_e32 v56, 16, v71
	v_and_b32_e32 v57, 0xffff0000, v71
	v_pk_mul_f32 v[54:55], v[54:55], v[56:57]
	v_lshlrev_b32_e32 v56, 16, v72
	v_and_b32_e32 v57, 0xffff0000, v72
	v_pk_mul_f32 v[56:57], v[44:45], v[56:57]
	v_lshlrev_b32_e32 v44, 16, v73
	v_and_b32_e32 v45, 0xffff0000, v73
	v_pk_mul_f32 v[58:59], v[46:47], v[44:45]
	v_cvt_pk_bf16_f32 v44, v52, v53
	v_cvt_pk_bf16_f32 v45, v54, v55
	v_cvt_pk_bf16_f32 v46, v56, v57
	v_cvt_pk_bf16_f32 v47, v58, v59
	global_store_dwordx4 v[78:79], v[44:47], off offset:256
	s_waitcnt vmcnt(7)
	s_nop 0
	v_lshlrev_b32_e32 v44, 16, v74
	v_and_b32_e32 v45, 0xffff0000, v74
	v_pk_mul_f32 v[44:45], v[48:49], v[44:45]
	v_lshlrev_b32_e32 v48, 16, v76
	v_and_b32_e32 v49, 0xffff0000, v76
	v_lshlrev_b32_e32 v46, 16, v75
	v_and_b32_e32 v47, 0xffff0000, v75
	v_pk_mul_f32 v[48:49], v[40:41], v[48:49]
	v_lshlrev_b32_e32 v40, 16, v77
	v_and_b32_e32 v41, 0xffff0000, v77
	v_pk_mul_f32 v[46:47], v[50:51], v[46:47]
	v_pk_mul_f32 v[50:51], v[42:43], v[40:41]
	v_cvt_pk_bf16_f32 v40, v44, v45
	v_cvt_pk_bf16_f32 v41, v46, v47
	v_cvt_pk_bf16_f32 v42, v48, v49
	v_cvt_pk_bf16_f32 v43, v50, v51
	global_store_dwordx4 v[102:103], v[40:43], off
	s_waitcnt vmcnt(7)
	s_nop 0
	v_lshlrev_b32_e32 v40, 16, v82
	v_and_b32_e32 v41, 0xffff0000, v82
	v_pk_mul_f32 v[36:37], v[36:37], v[40:41]
	v_lshlrev_b32_e32 v40, 16, v83
	v_and_b32_e32 v41, 0xffff0000, v83
	v_pk_mul_f32 v[38:39], v[38:39], v[40:41]
	v_lshlrev_b32_e32 v40, 16, v84
	v_and_b32_e32 v41, 0xffff0000, v84
	v_pk_mul_f32 v[40:41], v[28:29], v[40:41]
	v_lshlrev_b32_e32 v28, 16, v85
	v_and_b32_e32 v29, 0xffff0000, v85
	v_pk_mul_f32 v[42:43], v[30:31], v[28:29]
	v_cvt_pk_bf16_f32 v28, v36, v37
	v_cvt_pk_bf16_f32 v29, v38, v39
	v_cvt_pk_bf16_f32 v30, v40, v41
	v_cvt_pk_bf16_f32 v31, v42, v43
	global_store_dwordx4 v[102:103], v[28:31], off offset:256
	s_waitcnt vmcnt(7)
	s_nop 0
	v_lshlrev_b32_e32 v28, 16, v86
	v_and_b32_e32 v29, 0xffff0000, v86
	v_pk_mul_f32 v[28:29], v[32:33], v[28:29]
	v_lshlrev_b32_e32 v32, 16, v88
	v_and_b32_e32 v33, 0xffff0000, v88
	v_lshlrev_b32_e32 v30, 16, v87
	v_and_b32_e32 v31, 0xffff0000, v87
	v_pk_mul_f32 v[32:33], v[24:25], v[32:33]
	v_lshlrev_b32_e32 v24, 16, v89
	v_and_b32_e32 v25, 0xffff0000, v89
	v_pk_mul_f32 v[30:31], v[34:35], v[30:31]
	v_pk_mul_f32 v[34:35], v[26:27], v[24:25]
	v_cvt_pk_bf16_f32 v24, v28, v29
	v_cvt_pk_bf16_f32 v25, v30, v31
	v_cvt_pk_bf16_f32 v26, v32, v33
	v_cvt_pk_bf16_f32 v27, v34, v35
	global_store_dwordx4 v[104:105], v[24:27], off
	s_waitcnt vmcnt(7)
	s_nop 0
	v_lshlrev_b32_e32 v24, 16, v90
	v_and_b32_e32 v25, 0xffff0000, v90
	v_pk_mul_f32 v[20:21], v[20:21], v[24:25]
	v_lshlrev_b32_e32 v24, 16, v91
	v_and_b32_e32 v25, 0xffff0000, v91
	v_pk_mul_f32 v[22:23], v[22:23], v[24:25]
	v_lshlrev_b32_e32 v24, 16, v92
	v_and_b32_e32 v25, 0xffff0000, v92
	v_pk_mul_f32 v[24:25], v[12:13], v[24:25]
	v_lshlrev_b32_e32 v12, 16, v93
	v_and_b32_e32 v13, 0xffff0000, v93
	v_pk_mul_f32 v[26:27], v[14:15], v[12:13]
	v_cvt_pk_bf16_f32 v12, v20, v21
	v_cvt_pk_bf16_f32 v13, v22, v23
	v_cvt_pk_bf16_f32 v14, v24, v25
	v_cvt_pk_bf16_f32 v15, v26, v27
	global_store_dwordx4 v[104:105], v[12:15], off offset:256
	s_waitcnt vmcnt(7)
	s_nop 0
	v_lshlrev_b32_e32 v12, 16, v94
	v_and_b32_e32 v13, 0xffff0000, v94
	v_pk_mul_f32 v[12:13], v[16:17], v[12:13]
	v_lshlrev_b32_e32 v16, 16, v96
	v_and_b32_e32 v17, 0xffff0000, v96
	v_lshlrev_b32_e32 v14, 16, v95
	v_and_b32_e32 v15, 0xffff0000, v95
	v_pk_mul_f32 v[16:17], v[8:9], v[16:17]
	v_lshlrev_b32_e32 v8, 16, v97
	v_and_b32_e32 v9, 0xffff0000, v97
	v_pk_mul_f32 v[14:15], v[18:19], v[14:15]
	v_pk_mul_f32 v[18:19], v[10:11], v[8:9]
	v_cvt_pk_bf16_f32 v8, v12, v13
	v_cvt_pk_bf16_f32 v9, v14, v15
	v_cvt_pk_bf16_f32 v10, v16, v17
	v_cvt_pk_bf16_f32 v11, v18, v19
	global_store_dwordx4 v[64:65], v[8:11], off
	s_waitcnt vmcnt(7)
	s_nop 0
	v_lshlrev_b32_e32 v8, 16, v98
	v_and_b32_e32 v9, 0xffff0000, v98
	v_pk_mul_f32 v[4:5], v[4:5], v[8:9]
	v_lshlrev_b32_e32 v8, 16, v99
	v_and_b32_e32 v9, 0xffff0000, v99
	v_pk_mul_f32 v[6:7], v[6:7], v[8:9]
	v_lshlrev_b32_e32 v8, 16, v100
	v_and_b32_e32 v9, 0xffff0000, v100
	v_pk_mul_f32 v[8:9], v[0:1], v[8:9]
	v_lshlrev_b32_e32 v0, 16, v101
	v_and_b32_e32 v1, 0xffff0000, v101
	v_pk_mul_f32 v[10:11], v[2:3], v[0:1]
	v_cvt_pk_bf16_f32 v0, v4, v5
	v_cvt_pk_bf16_f32 v1, v6, v7
	v_cvt_pk_bf16_f32 v2, v8, v9
	v_cvt_pk_bf16_f32 v3, v10, v11
	global_store_dwordx4 v[64:65], v[0:3], off offset:256
	s_cbranch_vccnz .LBB0_1297
	s_andn2_b64 vcc, exec, s[4:5]
	s_cbranch_vccnz .LBB0_1296
	s_barrier
	s_branch .LBB0_1296

; #define PG8_STAGE(bufoff, gbase, voff) do { _Pragma("unroll") for (int _i = 0; _i < 2; ++_i) \
;         __builtin_amdgcn_global_load_lds((const unsigned*)((const char*)(gbase) + (voff)[_i]), (PG8_LAS unsigned*)(lds + (bufoff) + ldsw + _i * 8192), 16, 0, 0); } while (0)
; #define PG8_LDA(dst, b, h) do { _Pragma("unroll") for (int m = 0; m < 4; ++m) _Pragma("unroll") for (int k = 0; k < 2; ++k) dst[m][k] = *(const PG8_LAS bf16x8*)(lds + PG8_SA(b, h) + aoff + m * 2048 + k * 1024); } while (0)
; #define PG8_LDB(dst, b, h) do { _Pragma("unroll") for (int n = 0; n < 2; ++n) _Pragma("unroll") for (int k = 0; k < 2; ++k) dst[n][k] = *(const PG8_LAS bf16x8*)(lds + PG8_SB(b, h) + boff + n * 2048 + k * 1024); } while (0)
; #define PG8_MMA(ai, bj, At, Bt) do { __builtin_amdgcn_s_setprio(1); _Pragma("unroll") for (int m = 0; m < 4; ++m) _Pragma("unroll") for (int n = 0; n < 2; ++n) _Pragma("unroll") for (int k = 0; k < 2; ++k) \
;         acc[ai][bj][m][n] = __builtin_amdgcn_mfma_f32_16x16x32_bf16(Bt[n][k], At[m][k], acc[ai][bj][m][n], 0, 0, 0); __builtin_amdgcn_s_setprio(0); } while (0)
; #define PG8_WAIT_V(n) asm volatile("s_waitcnt vmcnt(" #n ")" ::: "memory")
; #define PG8_WAIT_L(n) asm volatile("s_waitcnt lgkmcnt(" #n ")" ::: "memory")
; #define PG8_BAR __builtin_amdgcn_s_barrier()
; #define PG8_SCHED __builtin_amdgcn_sched_barrier(0)
; template <class Epi, class Sched, bool ALIGN_EPI = false, bool SP2 = false>
; __device__ __forceinline__ void gemm_phase(PG8_LAS unsigned char* lds, const Gemm g, const Sched& S, const Epi& E, int tid_in) {
;     ...
;             PG8_LDB(B0, 0, 0); PG8_LDB(B1, 0, 1); PG8_SCHED; PG8_LDA(At, 0, 0); PG8_STAGE(PG8_SA(1, 1), a1 + hstep, voffA);
;             PG8_WAIT_V(8); PG8_WAIT_L(0); PG8_BAR; PG8_MMA(0, 0, At, B0); PG8_MMA(0, 1, At, B1); PG8_BAR; PG8_SCHED;
;             PG8_LDA(At, 0, 1); PG8_STAGE(PG8_SB(0, 0), b2, voffB); PG8_STAGE(PG8_SB(0, 1), b2 + hstep, voffB); PG8_STAGE(PG8_SA(0, 0), a2, voffA);
.LBB0_1340:
	s_add_u32 s54, s52, 0xfffc0080
	s_addc_u32 s55, s53, -1
	s_add_i32 s66, 0, 0x10000
	s_cmp_eq_u32 s65, 12
	s_cselect_b32 s57, s0, s55
	s_cselect_b32 s56, s1, s54
	s_cselect_b32 s55, s41, s64
	s_cselect_b32 s54, s45, s63
	s_add_i32 s68, 0, 0x14000
	v_add_u32_e32 v142, s66, v214
	v_add_u32_e32 v158, s68, v214
	ds_read_b128 v[130:133], v142
	ds_read_b128 v[134:137], v142 offset:1024
	ds_read_b128 v[138:141], v142 offset:2048
	ds_read_b128 v[142:145], v142 offset:3072
	ds_read_b128 v[146:149], v158
	ds_read_b128 v[150:153], v158 offset:1024
	ds_read_b128 v[154:157], v158 offset:2048
	ds_read_b128 v[158:161], v158 offset:3072
	v_lshl_add_u64 v[186:187], s[52:53], 0, v[196:197]
	s_add_i32 m0, s16, 0xc000
	ds_read_b128 v[162:165], v215
	ds_read_b128 v[166:169], v215 offset:1024
	ds_read_b128 v[170:173], v215 offset:2048
	ds_read_b128 v[174:177], v215 offset:3072
	ds_read_b128 v[178:181], v215 offset:4096
	ds_read_b128 v[182:185], v215 offset:5120
	ds_read_b128 v[200:203], v215 offset:6144
	ds_read_b128 v[204:207], v215 offset:7168
	global_load_lds_dwordx4 v[186:187], off
	v_lshl_add_u64 v[186:187], s[52:53], 0, v[198:199]
	s_add_i32 m0, s16, 0xe000
	s_nop 0
	global_load_lds_dwordx4 v[186:187], off
	s_waitcnt vmcnt(8)
	s_waitcnt lgkmcnt(0)
	s_barrier
	s_setprio 1
	s_waitcnt lgkmcnt(0)
	v_mfma_f32_16x16x32_bf16 v[126:129], v[130:133], v[162:165], v[126:129]
	v_mfma_f32_16x16x32_bf16 v[122:125], v[138:141], v[162:165], v[122:125]
	v_mfma_f32_16x16x32_bf16 v[110:113], v[130:133], v[170:173], v[110:113]
	v_mfma_f32_16x16x32_bf16 v[106:109], v[138:141], v[170:173], v[106:109]
	v_mfma_f32_16x16x32_bf16 v[94:97], v[130:133], v[178:181], v[94:97]
	v_mfma_f32_16x16x32_bf16 v[90:93], v[138:141], v[178:181], v[90:93]
	v_mfma_f32_16x16x32_bf16 v[76:79], v[130:133], v[200:203], v[76:79]
	v_mfma_f32_16x16x32_bf16 v[72:75], v[138:141], v[200:203], v[72:75]
	v_mfma_f32_16x16x32_bf16 v[126:129], v[134:137], v[166:169], v[126:129]
	v_mfma_f32_16x16x32_bf16 v[122:125], v[142:145], v[166:169], v[122:125]
	v_mfma_f32_16x16x32_bf16 v[110:113], v[134:137], v[174:177], v[110:113]
	v_mfma_f32_16x16x32_bf16 v[106:109], v[142:145], v[174:177], v[106:109]
	v_mfma_f32_16x16x32_bf16 v[94:97], v[134:137], v[182:185], v[94:97]
	v_mfma_f32_16x16x32_bf16 v[90:93], v[142:145], v[182:185], v[90:93]
	v_mfma_f32_16x16x32_bf16 v[76:79], v[134:137], v[204:207], v[76:79]
	v_mfma_f32_16x16x32_bf16 v[72:75], v[142:145], v[204:207], v[72:75]
	v_mfma_f32_16x16x32_bf16 v[118:121], v[146:149], v[162:165], v[118:121]
	v_mfma_f32_16x16x32_bf16 v[114:117], v[154:157], v[162:165], v[114:117]
	v_mfma_f32_16x16x32_bf16 v[102:105], v[146:149], v[170:173], v[102:105]
	v_mfma_f32_16x16x32_bf16 v[98:101], v[154:157], v[170:173], v[98:101]
	v_mfma_f32_16x16x32_bf16 v[86:89], v[146:149], v[178:181], v[86:89]
	v_mfma_f32_16x16x32_bf16 v[82:85], v[154:157], v[178:181], v[82:85]
	v_mfma_f32_16x16x32_bf16 v[68:71], v[146:149], v[200:203], v[68:71]
	v_mfma_f32_16x16x32_bf16 v[64:67], v[154:157], v[200:203], v[64:67]
	v_mfma_f32_16x16x32_bf16 v[118:121], v[150:153], v[166:169], v[118:121]
	v_mfma_f32_16x16x32_bf16 v[114:117], v[158:161], v[166:169], v[114:117]
	v_mfma_f32_16x16x32_bf16 v[102:105], v[150:153], v[174:177], v[102:105]
	v_mfma_f32_16x16x32_bf16 v[98:101], v[158:161], v[174:177], v[98:101]
	v_mfma_f32_16x16x32_bf16 v[86:89], v[150:153], v[182:185], v[86:89]
	v_mfma_f32_16x16x32_bf16 v[82:85], v[158:161], v[182:185], v[82:85]
	v_mfma_f32_16x16x32_bf16 v[68:71], v[150:153], v[204:207], v[68:71]
	v_mfma_f32_16x16x32_bf16 v[64:67], v[158:161], v[204:207], v[64:67]
	s_setprio 0
	s_barrier
	s_add_i32 s66, s66, s15
	v_lshl_add_u64 v[186:187], s[54:55], 0, v[80:81]
	s_mov_b32 m0, s66
	ds_read_b128 v[162:165], v215 offset:16384
	ds_read_b128 v[166:169], v215 offset:17408
	ds_read_b128 v[170:173], v215 offset:18432
	ds_read_b128 v[174:177], v215 offset:19456
	ds_read_b128 v[178:181], v215 offset:20480
	ds_read_b128 v[182:185], v215 offset:21504
	ds_read_b128 v[200:203], v215 offset:22528
	ds_read_b128 v[204:207], v215 offset:23552
	global_load_lds_dwordx4 v[186:187], off
	s_add_i32 m0, s66, 0x2000
	s_add_u32 s66, s54, 0x40000
	v_lshl_add_u64 v[188:189], s[54:55], 0, v[194:195]
	s_addc_u32 s67, s55, 0
	s_add_i32 s68, s68, s15
	global_load_lds_dwordx4 v[188:189], off
	v_lshl_add_u64 v[208:209], s[66:67], 0, v[80:81]
	s_mov_b32 m0, s68
	v_lshl_add_u64 v[210:211], s[56:57], 0, v[192:193]
	global_load_lds_dwordx4 v[208:209], off
	v_lshl_add_u64 v[208:209], s[66:67], 0, v[194:195]
	s_add_i32 m0, s68, 0x2000
	s_nop 0
	global_load_lds_dwordx4 v[208:209], off
	v_lshl_add_u64 v[208:209], s[56:57], 0, v[190:191]
	s_mov_b32 m0, s16
	s_nop 0
	global_load_lds_dwordx4 v[208:209], off
	s_mov_b32 m0, s17
	s_nop 0
	global_load_lds_dwordx4 v[210:211], off
	s_waitcnt vmcnt(8)
	s_waitcnt lgkmcnt(0)
	s_barrier
; #define PG8_STAGE(bufoff, gbase, voff) do { _Pragma("unroll") for (int _i = 0; _i < 2; ++_i) \
;         __builtin_amdgcn_global_load_lds((const unsigned*)((const char*)(gbase) + (voff)[_i]), (PG8_LAS unsigned*)(lds + (bufoff) + ldsw + _i * 8192), 16, 0, 0); } while (0)
; #define PG8_LDA(dst, b, h) do { _Pragma("unroll") for (int m = 0; m < 4; ++m) _Pragma("unroll") for (int k = 0; k < 2; ++k) dst[m][k] = *(const PG8_LAS bf16x8*)(lds + PG8_SA(b, h) + aoff + m * 2048 + k * 1024); } while (0)
; #define PG8_LDB(dst, b, h) do { _Pragma("unroll") for (int n = 0; n < 2; ++n) _Pragma("unroll") for (int k = 0; k < 2; ++k) dst[n][k] = *(const PG8_LAS bf16x8*)(lds + PG8_SB(b, h) + boff + n * 2048 + k * 1024); } while (0)
; #define PG8_MMA(ai, bj, At, Bt) do { __builtin_amdgcn_s_setprio(1); _Pragma("unroll") for (int m = 0; m < 4; ++m) _Pragma("unroll") for (int n = 0; n < 2; ++n) _Pragma("unroll") for (int k = 0; k < 2; ++k) \
;         acc[ai][bj][m][n] = __builtin_amdgcn_mfma_f32_16x16x32_bf16(Bt[n][k], At[m][k], acc[ai][bj][m][n], 0, 0, 0); __builtin_amdgcn_s_setprio(0); } while (0)
; #define PG8_WAIT_V(n) asm volatile("s_waitcnt vmcnt(" #n ")" ::: "memory")
; #define PG8_WAIT_L(n) asm volatile("s_waitcnt lgkmcnt(" #n ")" ::: "memory")
; #define PG8_BAR __builtin_amdgcn_s_barrier()
; #define PG8_SCHED __builtin_amdgcn_sched_barrier(0)
; template <class Epi, class Sched, bool ALIGN_EPI = false, bool SP2 = false>
; __device__ __forceinline__ void gemm_phase(PG8_LAS unsigned char* lds, const Gemm g, const Sched& S, const Epi& E, int tid_in) {
;     ...
;             PG8_WAIT_V(8); PG8_WAIT_L(0); PG8_BAR; PG8_MMA(1, 0, At, B0); PG8_MMA(1, 1, At, B1); PG8_BAR; PG8_SCHED;
;             PG8_LDB(B0, 1, 0); PG8_LDB(B1, 1, 1); PG8_SCHED; PG8_LDA(At, 1, 0); PG8_STAGE(PG8_SA(0, 1), a2 + hstep, voffA);
;             PG8_WAIT_V(8); PG8_WAIT_L(0); PG8_BAR; PG8_MMA(0, 0, At, B0); PG8_MMA(0, 1, At, B1); PG8_BAR; PG8_SCHED;
	s_setprio 1
	s_waitcnt lgkmcnt(0)
	v_mfma_f32_16x16x32_bf16 v[60:63], v[130:133], v[162:165], v[60:63]
	v_mfma_f32_16x16x32_bf16 v[56:59], v[138:141], v[162:165], v[56:59]
	v_mfma_f32_16x16x32_bf16 v[44:47], v[130:133], v[170:173], v[44:47]
	v_mfma_f32_16x16x32_bf16 v[40:43], v[138:141], v[170:173], v[40:43]
	v_mfma_f32_16x16x32_bf16 v[28:31], v[130:133], v[178:181], v[28:31]
	v_mfma_f32_16x16x32_bf16 v[24:27], v[138:141], v[178:181], v[24:27]
	v_mfma_f32_16x16x32_bf16 v[12:15], v[130:133], v[200:203], v[12:15]
	v_mfma_f32_16x16x32_bf16 v[8:11], v[138:141], v[200:203], v[8:11]
	v_mfma_f32_16x16x32_bf16 v[60:63], v[134:137], v[166:169], v[60:63]
	v_mfma_f32_16x16x32_bf16 v[56:59], v[142:145], v[166:169], v[56:59]
	v_mfma_f32_16x16x32_bf16 v[44:47], v[134:137], v[174:177], v[44:47]
	v_mfma_f32_16x16x32_bf16 v[40:43], v[142:145], v[174:177], v[40:43]
	v_mfma_f32_16x16x32_bf16 v[28:31], v[134:137], v[182:185], v[28:31]
	v_mfma_f32_16x16x32_bf16 v[24:27], v[142:145], v[182:185], v[24:27]
	v_mfma_f32_16x16x32_bf16 v[12:15], v[134:137], v[204:207], v[12:15]
	v_mfma_f32_16x16x32_bf16 v[8:11], v[142:145], v[204:207], v[8:11]
	v_mfma_f32_16x16x32_bf16 v[52:55], v[146:149], v[162:165], v[52:55]
	v_mfma_f32_16x16x32_bf16 v[48:51], v[154:157], v[162:165], v[48:51]
	v_mfma_f32_16x16x32_bf16 v[36:39], v[146:149], v[170:173], v[36:39]
	v_mfma_f32_16x16x32_bf16 v[32:35], v[154:157], v[170:173], v[32:35]
	v_mfma_f32_16x16x32_bf16 v[20:23], v[146:149], v[178:181], v[20:23]
	v_mfma_f32_16x16x32_bf16 v[16:19], v[154:157], v[178:181], v[16:19]
	v_mfma_f32_16x16x32_bf16 v[4:7], v[146:149], v[200:203], v[4:7]
	v_mfma_f32_16x16x32_bf16 v[0:3], v[154:157], v[200:203], v[0:3]
	v_mfma_f32_16x16x32_bf16 v[52:55], v[150:153], v[166:169], v[52:55]
	v_mfma_f32_16x16x32_bf16 v[48:51], v[158:161], v[166:169], v[48:51]
	v_mfma_f32_16x16x32_bf16 v[36:39], v[150:153], v[174:177], v[36:39]
	v_mfma_f32_16x16x32_bf16 v[32:35], v[158:161], v[174:177], v[32:35]
	v_mfma_f32_16x16x32_bf16 v[20:23], v[150:153], v[182:185], v[20:23]
	v_mfma_f32_16x16x32_bf16 v[16:19], v[158:161], v[182:185], v[16:19]
	v_mfma_f32_16x16x32_bf16 v[4:7], v[150:153], v[204:207], v[4:7]
	v_mfma_f32_16x16x32_bf16 v[0:3], v[158:161], v[204:207], v[0:3]
	s_setprio 0
	s_barrier
	s_add_i32 s66, 0, 0x18000
	s_add_i32 s67, 0, 0x1c000
	v_add_u32_e32 v142, s66, v214
	v_add_u32_e32 v158, s67, v214
	ds_read_b128 v[130:133], v142
	ds_read_b128 v[134:137], v142 offset:1024
	ds_read_b128 v[138:141], v142 offset:2048
	ds_read_b128 v[142:145], v142 offset:3072
	ds_read_b128 v[146:149], v158
	ds_read_b128 v[150:153], v158 offset:1024
	ds_read_b128 v[154:157], v158 offset:2048
	ds_read_b128 v[158:161], v158 offset:3072
	s_add_u32 s56, s56, 0x40000
	s_addc_u32 s57, s57, 0
	s_mov_b32 m0, s18
	v_lshl_add_u64 v[226:227], s[56:57], 0, v[190:191]
	ds_read_b128 v[162:165], v215 offset:32768
	ds_read_b128 v[166:169], v215 offset:33792
	ds_read_b128 v[170:173], v215 offset:34816
	ds_read_b128 v[174:177], v215 offset:35840
	ds_read_b128 v[178:181], v215 offset:36864
	ds_read_b128 v[182:185], v215 offset:37888
	ds_read_b128 v[200:203], v215 offset:38912
	ds_read_b128 v[204:207], v215 offset:39936
	global_load_lds_dwordx4 v[226:227], off
	v_lshl_add_u64 v[226:227], s[56:57], 0, v[192:193]
	s_mov_b32 m0, s19
	s_nop 0
	global_load_lds_dwordx4 v[226:227], off
	s_waitcnt vmcnt(8)
	s_waitcnt lgkmcnt(0)
	s_barrier
	s_setprio 1
	s_waitcnt lgkmcnt(0)
	v_mfma_f32_16x16x32_bf16 v[126:129], v[130:133], v[162:165], v[126:129]
	v_mfma_f32_16x16x32_bf16 v[122:125], v[138:141], v[162:165], v[122:125]
	v_mfma_f32_16x16x32_bf16 v[110:113], v[130:133], v[170:173], v[110:113]
	v_mfma_f32_16x16x32_bf16 v[106:109], v[138:141], v[170:173], v[106:109]
	v_mfma_f32_16x16x32_bf16 v[94:97], v[130:133], v[178:181], v[94:97]
	v_mfma_f32_16x16x32_bf16 v[90:93], v[138:141], v[178:181], v[90:93]
	v_mfma_f32_16x16x32_bf16 v[76:79], v[130:133], v[200:203], v[76:79]
	v_mfma_f32_16x16x32_bf16 v[72:75], v[138:141], v[200:203], v[72:75]
	v_mfma_f32_16x16x32_bf16 v[126:129], v[134:137], v[166:169], v[126:129]
	v_mfma_f32_16x16x32_bf16 v[122:125], v[142:145], v[166:169], v[122:125]
	v_mfma_f32_16x16x32_bf16 v[110:113], v[134:137], v[174:177], v[110:113]
	v_mfma_f32_16x16x32_bf16 v[106:109], v[142:145], v[174:177], v[106:109]
	v_mfma_f32_16x16x32_bf16 v[94:97], v[134:137], v[182:185], v[94:97]
	v_mfma_f32_16x16x32_bf16 v[90:93], v[142:145], v[182:185], v[90:93]
	v_mfma_f32_16x16x32_bf16 v[76:79], v[134:137], v[204:207], v[76:79]
	v_mfma_f32_16x16x32_bf16 v[72:75], v[142:145], v[204:207], v[72:75]
	v_mfma_f32_16x16x32_bf16 v[118:121], v[146:149], v[162:165], v[118:121]
	v_mfma_f32_16x16x32_bf16 v[114:117], v[154:157], v[162:165], v[114:117]
	v_mfma_f32_16x16x32_bf16 v[102:105], v[146:149], v[170:173], v[102:105]
	v_mfma_f32_16x16x32_bf16 v[98:101], v[154:157], v[170:173], v[98:101]
	v_mfma_f32_16x16x32_bf16 v[86:89], v[146:149], v[178:181], v[86:89]
	v_mfma_f32_16x16x32_bf16 v[82:85], v[154:157], v[178:181], v[82:85]
	v_mfma_f32_16x16x32_bf16 v[68:71], v[146:149], v[200:203], v[68:71]
	v_mfma_f32_16x16x32_bf16 v[64:67], v[154:157], v[200:203], v[64:67]
	v_mfma_f32_16x16x32_bf16 v[118:121], v[150:153], v[166:169], v[118:121]
	v_mfma_f32_16x16x32_bf16 v[114:117], v[158:161], v[166:169], v[114:117]
	v_mfma_f32_16x16x32_bf16 v[102:105], v[150:153], v[174:177], v[102:105]
	v_mfma_f32_16x16x32_bf16 v[98:101], v[158:161], v[174:177], v[98:101]
	v_mfma_f32_16x16x32_bf16 v[86:89], v[150:153], v[182:185], v[86:89]
	v_mfma_f32_16x16x32_bf16 v[82:85], v[158:161], v[182:185], v[82:85]
	v_mfma_f32_16x16x32_bf16 v[68:71], v[150:153], v[204:207], v[68:71]
	v_mfma_f32_16x16x32_bf16 v[64:67], v[158:161], v[204:207], v[64:67]
	s_setprio 0
	s_barrier
; #define PG8_STAGE(bufoff, gbase, voff) do { _Pragma("unroll") for (int _i = 0; _i < 2; ++_i) \
;         __builtin_amdgcn_global_load_lds((const unsigned*)((const char*)(gbase) + (voff)[_i]), (PG8_LAS unsigned*)(lds + (bufoff) + ldsw + _i * 8192), 16, 0, 0); } while (0)
; #define PG8_LDA(dst, b, h) do { _Pragma("unroll") for (int m = 0; m < 4; ++m) _Pragma("unroll") for (int k = 0; k < 2; ++k) dst[m][k] = *(const PG8_LAS bf16x8*)(lds + PG8_SA(b, h) + aoff + m * 2048 + k * 1024); } while (0)
; #define PG8_MMA(ai, bj, At, Bt) do { __builtin_amdgcn_s_setprio(1); _Pragma("unroll") for (int m = 0; m < 4; ++m) _Pragma("unroll") for (int n = 0; n < 2; ++n) _Pragma("unroll") for (int k = 0; k < 2; ++k) \
;         acc[ai][bj][m][n] = __builtin_amdgcn_mfma_f32_16x16x32_bf16(Bt[n][k], At[m][k], acc[ai][bj][m][n], 0, 0, 0); __builtin_amdgcn_s_setprio(0); } while (0)
; #define PG8_WAIT_V(n) asm volatile("s_waitcnt vmcnt(" #n ")" ::: "memory")
; #define PG8_WAIT_L(n) asm volatile("s_waitcnt lgkmcnt(" #n ")" ::: "memory")
; #define PG8_BAR __builtin_amdgcn_s_barrier()
; #define PG8_SCHED __builtin_amdgcn_sched_barrier(0)
; template <class Epi, class Sched, bool ALIGN_EPI = false, bool SP2 = false>
; __device__ __forceinline__ void gemm_phase(PG8_LAS unsigned char* lds, const Gemm g, const Sched& S, const Epi& E, int tid_in) {
;     ...
;             PG8_LDA(At, 1, 1); PG8_STAGE(PG8_SB(1, 0), b3, voffB); PG8_STAGE(PG8_SB(1, 1), b3 + hstep, voffB); PG8_STAGE(PG8_SA(1, 0), a3, voffA);
;             PG8_WAIT_V(8); PG8_WAIT_L(0); PG8_BAR; PG8_MMA(1, 0, At, B0); PG8_MMA(1, 1, At, B1); PG8_BAR; PG8_SCHED;
;     __device__ __forceinline__ void operator()(const pg8::f32x4 (&acc)[2][2][4][2], const pg8::Unit& u, int wr, int wc, int fr, int fq) const {
;     ...
;             u32x4 sv[4][2], av[4][2];
;             const size_t off0 = (size_t)(u.pm * 256 + ai * 128 + wr * 64 + fr) * 1024 + u.pn * 256 + wc * 32 + 8 * fq;
; #pragma unroll
;             for (int m = 0; m < 4; ++m)
; #pragma unroll
;                 for (int bj = 0; bj < 2; ++bj) { sv[m][bj] = *(const u32x4*)(S + off0 + (size_t)m * 16 * 1024 + bj * 128); if (ADD) av[m][bj] = *(const u32x4*)(A + off0 + (size_t)m * 16 * 1024 + bj * 128); }
	s_add_i32 s56, s66, s15
	v_lshl_add_u64 v[186:187], v[186:187], 0, s[6:7]
	s_mov_b32 m0, s56
	ds_read_b128 v[162:165], v215 offset:49152
	ds_read_b128 v[166:169], v215 offset:50176
	ds_read_b128 v[170:173], v215 offset:51200
	ds_read_b128 v[174:177], v215 offset:52224
	ds_read_b128 v[178:181], v215 offset:53248
	ds_read_b128 v[182:185], v215 offset:54272
	ds_read_b128 v[200:203], v215 offset:55296
	ds_read_b128 v[204:207], v215 offset:56320
	global_load_lds_dwordx4 v[186:187], off
	s_add_i32 m0, s56, 0x2000
	s_add_u32 s54, s54, 0x40080
	v_lshl_add_u64 v[186:187], v[188:189], 0, s[6:7]
	s_addc_u32 s55, s55, 0
	s_add_i32 s56, s67, s15
	global_load_lds_dwordx4 v[186:187], off
	v_lshl_add_u64 v[186:187], s[54:55], 0, v[80:81]
	s_mov_b32 m0, s56
	s_nop 0
	global_load_lds_dwordx4 v[186:187], off
	v_lshl_add_u64 v[186:187], s[54:55], 0, v[194:195]
	s_add_i32 m0, s56, 0x2000
	s_nop 0
	global_load_lds_dwordx4 v[186:187], off
	v_lshl_add_u64 v[186:187], v[208:209], 0, s[6:7]
	s_mov_b32 m0, s58
	s_nop 0
	global_load_lds_dwordx4 v[186:187], off
	v_lshl_add_u64 v[186:187], v[210:211], 0, s[6:7]
	s_mov_b32 m0, s59
	s_nop 0
	global_load_lds_dwordx4 v[186:187], off
	s_waitcnt vmcnt(8)
	s_waitcnt lgkmcnt(0)
	s_barrier
	s_setprio 1
	s_waitcnt lgkmcnt(0)
	v_mfma_f32_16x16x32_bf16 v[60:63], v[130:133], v[162:165], v[60:63]
	v_mfma_f32_16x16x32_bf16 v[56:59], v[138:141], v[162:165], v[56:59]
	v_mfma_f32_16x16x32_bf16 v[44:47], v[130:133], v[170:173], v[44:47]
	v_mfma_f32_16x16x32_bf16 v[40:43], v[138:141], v[170:173], v[40:43]
	v_mfma_f32_16x16x32_bf16 v[28:31], v[130:133], v[178:181], v[28:31]
	v_mfma_f32_16x16x32_bf16 v[24:27], v[138:141], v[178:181], v[24:27]
	v_mfma_f32_16x16x32_bf16 v[12:15], v[130:133], v[200:203], v[12:15]
	v_mfma_f32_16x16x32_bf16 v[8:11], v[138:141], v[200:203], v[8:11]
	v_mfma_f32_16x16x32_bf16 v[60:63], v[134:137], v[166:169], v[60:63]
	v_mfma_f32_16x16x32_bf16 v[56:59], v[142:145], v[166:169], v[56:59]
	v_mfma_f32_16x16x32_bf16 v[44:47], v[134:137], v[174:177], v[44:47]
	v_mfma_f32_16x16x32_bf16 v[40:43], v[142:145], v[174:177], v[40:43]
	v_mfma_f32_16x16x32_bf16 v[28:31], v[134:137], v[182:185], v[28:31]
	v_mfma_f32_16x16x32_bf16 v[24:27], v[142:145], v[182:185], v[24:27]
	v_mfma_f32_16x16x32_bf16 v[12:15], v[134:137], v[204:207], v[12:15]
	v_mfma_f32_16x16x32_bf16 v[8:11], v[142:145], v[204:207], v[8:11]
	v_mfma_f32_16x16x32_bf16 v[52:55], v[146:149], v[162:165], v[52:55]
	v_mfma_f32_16x16x32_bf16 v[48:51], v[154:157], v[162:165], v[48:51]
	v_mfma_f32_16x16x32_bf16 v[36:39], v[146:149], v[170:173], v[36:39]
	v_mfma_f32_16x16x32_bf16 v[32:35], v[154:157], v[170:173], v[32:35]
	v_mfma_f32_16x16x32_bf16 v[20:23], v[146:149], v[178:181], v[20:23]
	v_mfma_f32_16x16x32_bf16 v[16:19], v[154:157], v[178:181], v[16:19]
	v_mfma_f32_16x16x32_bf16 v[4:7], v[146:149], v[200:203], v[4:7]
	v_mfma_f32_16x16x32_bf16 v[0:3], v[154:157], v[200:203], v[0:3]
	v_mfma_f32_16x16x32_bf16 v[52:55], v[150:153], v[166:169], v[52:55]
	v_mfma_f32_16x16x32_bf16 v[48:51], v[158:161], v[166:169], v[48:51]
	v_mfma_f32_16x16x32_bf16 v[36:39], v[150:153], v[174:177], v[36:39]
	v_mfma_f32_16x16x32_bf16 v[32:35], v[158:161], v[174:177], v[32:35]
	v_mfma_f32_16x16x32_bf16 v[20:23], v[150:153], v[182:185], v[20:23]
	v_mfma_f32_16x16x32_bf16 v[16:19], v[158:161], v[182:185], v[16:19]
	v_mfma_f32_16x16x32_bf16 v[4:7], v[150:153], v[204:207], v[4:7]
	v_mfma_f32_16x16x32_bf16 v[0:3], v[158:161], v[204:207], v[0:3]
	s_setprio 0
	s_barrier
	s_add_i32 s65, s65, 2
	s_add_u32 s52, s52, 0x100
	s_addc_u32 s53, s53, 0
	s_add_u32 s63, s63, 0x100
	s_addc_u32 s64, s64, 0
	s_cmp_gt_u32 s65, 13
	s_cbranch_scc0 .LBB0_1340
	s_lshl_b32 s0, s50, 8
	v_mov_b32_e32 v130, v212
	v_mov_b32_e32 v131, v213
	s_add_i32 s0, s0, s51
	s_mov_b64 s[68:69], s[70:71]
	v_add_u32_e32 v200, s0, v130
	s_lshl_b32 s0, s62, 8
	s_ashr_i32 s1, s0, 31
	v_lshlrev_b32_e32 v130, 3, v131
	v_ashrrev_i32_e32 v131, 31, v130
	s_or_b64 s[0:1], s[0:1], s[70:71]
	v_ashrrev_i32_e32 v201, 31, v200
	v_lshl_add_u64 v[202:203], s[0:1], 0, v[130:131]
	v_lshlrev_b64 v[130:131], 10, v[200:201]
	v_lshl_add_u64 v[130:131], v[202:203], 0, v[130:131]
	v_lshlrev_b64 v[130:131], 1, v[130:131]
	v_lshl_add_u64 v[210:211], s[84:85], 0, v[130:131]
	v_lshl_add_u64 v[130:131], s[80:81], 0, v[130:131]
	global_load_dwordx4 v[234:237], v[210:211], off
	global_load_dwordx4 v[238:241], v[130:131], off
	global_load_dwordx4 v[182:185], v[210:211], off offset:256
	global_load_dwordx4 v[178:181], v[130:131], off offset:256
	v_add_co_u32_e32 v208, vcc, s11, v210
	s_mov_b64 s[0:1], -1
	s_nop 0
	v_addc_co_u32_e32 v209, vcc, 0, v211, vcc
	global_load_dwordx4 v[170:173], v[208:209], off
	v_add_co_u32_e32 v132, vcc, s11, v130
	s_nop 0
	v_addc_co_u32_e32 v133, vcc, 0, v131, vcc
	global_load_dwordx4 v[174:177], v[132:133], off
	global_load_dwordx4 v[166:169], v[208:209], off offset:256
	global_load_dwordx4 v[162:165], v[132:133], off offset:256
	v_add_co_u32_e32 v206, vcc, s33, v210
	s_nop 0
	v_addc_co_u32_e32 v207, vcc, 0, v211, vcc
	global_load_dwordx4 v[154:157], v[206:207], off
	v_add_co_u32_e32 v132, vcc, s33, v130
	s_nop 0
	v_addc_co_u32_e32 v133, vcc, 0, v131, vcc
	global_load_dwordx4 v[158:161], v[132:133], off
	global_load_dwordx4 v[150:153], v[206:207], off offset:256
	global_load_dwordx4 v[146:149], v[132:133], off offset:256
	v_add_co_u32_e32 v204, vcc, s10, v210
	s_nop 0
	v_addc_co_u32_e32 v205, vcc, 0, v211, vcc
	global_load_dwordx4 v[138:141], v[204:205], off
	v_add_co_u32_e32 v130, vcc, s10, v130
	s_nop 0
	v_addc_co_u32_e32 v131, vcc, 0, v131, vcc
	global_load_dwordx4 v[142:145], v[130:131], off
	global_load_dwordx4 v[134:137], v[204:205], off offset:256
	s_nop 0
	global_load_dwordx4 v[130:133], v[130:131], off offset:256
	s_and_b64 vcc, exec, s[8:9]
	s_cbranch_vccz .LBB0_1343
	s_barrier
; __device__ __forceinline__ float bflo(unsigned w) { return __uint_as_float(w << 16); }
; __device__ __forceinline__ float bfhi(unsigned w) { return __uint_as_float(w & 0xffff0000u); }
; __device__ __forceinline__ u32x4 pack8(f32x4 a, f32x4 b) { u32x4 w; w.x = cvtpk(a[0], a[1]); w.y = cvtpk(a[2], a[3]); w.z = cvtpk(b[0], b[1]); w.w = cvtpk(b[2], b[3]); return w; }
;     __device__ __forceinline__ void operator()(const pg8::f32x4 (&acc)[2][2][4][2], const pg8::Unit& u, int wr, int wc, int fr, int fq) const {
;     ...
;             for (int m = 0; m < 4; ++m)
; #pragma unroll
;                 for (int bj = 0; bj < 2; ++bj) {
;                     const u32x4 s = sv[m][bj];
;                     f32x4 v0 = acc[ai][bj][m][0], v1 = acc[ai][bj][m][1];
;                     v0[0] *= bflo(s.x); v0[1] *= bfhi(s.x); v0[2] *= bflo(s.y); v0[3] *= bfhi(s.y); v1[0] *= bflo(s.z); v1[1] *= bfhi(s.z); v1[2] *= bflo(s.w); v1[3] *= bfhi(s.w);
;                     if (ADD) { const u32x4 a = av[m][bj];
;                         v0[0] += bflo(a.x); v0[1] += bfhi(a.x); v0[2] += bflo(a.y); v0[3] += bfhi(a.y); v1[0] += bflo(a.z); v1[1] += bfhi(a.z); v1[2] += bflo(a.w); v1[3] += bfhi(a.w); }
;                     *(u32x4*)(S + off0 + (size_t)m * 16 * 1024 + bj * 128) = pack8(v0, v1);
;                 }
.LBB0_1343:
	s_waitcnt vmcnt(11)
	v_lshlrev_b32_e32 v186, 16, v234
	v_and_b32_e32 v187, 0xffff0000, v234
	v_lshlrev_b32_e32 v188, 16, v238
	v_and_b32_e32 v189, 0xffff0000, v238
	v_pk_fma_f32 v[126:127], v[126:127], v[186:187], v[188:189]
	v_lshlrev_b32_e32 v186, 16, v235
	v_and_b32_e32 v187, 0xffff0000, v235
	v_lshlrev_b32_e32 v188, 16, v239
	v_and_b32_e32 v189, 0xffff0000, v239
	v_pk_fma_f32 v[128:129], v[128:129], v[186:187], v[188:189]
	v_lshlrev_b32_e32 v186, 16, v236
	v_and_b32_e32 v187, 0xffff0000, v236
	v_lshlrev_b32_e32 v188, 16, v240
	v_and_b32_e32 v189, 0xffff0000, v240
	v_pk_fma_f32 v[186:187], v[122:123], v[186:187], v[188:189]
	v_lshlrev_b32_e32 v122, 16, v237
	v_and_b32_e32 v123, 0xffff0000, v237
	v_lshlrev_b32_e32 v188, 16, v241
	v_and_b32_e32 v189, 0xffff0000, v241
	v_pk_fma_f32 v[188:189], v[124:125], v[122:123], v[188:189]
	v_cvt_pk_bf16_f32 v122, v126, v127
	v_cvt_pk_bf16_f32 v123, v128, v129
	v_cvt_pk_bf16_f32 v124, v186, v187
	v_cvt_pk_bf16_f32 v125, v188, v189
	global_store_dwordx4 v[210:211], v[122:125], off
	s_nop 1
	v_lshlrev_b32_e32 v122, 16, v182
	v_and_b32_e32 v123, 0xffff0000, v182
	v_lshlrev_b32_e32 v124, 16, v178
	v_and_b32_e32 v125, 0xffff0000, v178
	v_pk_fma_f32 v[118:119], v[118:119], v[122:123], v[124:125]
	v_lshlrev_b32_e32 v122, 16, v183
	v_and_b32_e32 v123, 0xffff0000, v183
	v_lshlrev_b32_e32 v124, 16, v179
	v_and_b32_e32 v125, 0xffff0000, v179
	v_pk_fma_f32 v[120:121], v[120:121], v[122:123], v[124:125]
	v_lshlrev_b32_e32 v122, 16, v184
	v_and_b32_e32 v123, 0xffff0000, v184
	v_lshlrev_b32_e32 v124, 16, v180
	v_and_b32_e32 v125, 0xffff0000, v180
	v_pk_fma_f32 v[122:123], v[114:115], v[122:123], v[124:125]
	v_lshlrev_b32_e32 v114, 16, v185
	v_and_b32_e32 v115, 0xffff0000, v185
	v_lshlrev_b32_e32 v124, 16, v181
	v_and_b32_e32 v125, 0xffff0000, v181
	v_pk_fma_f32 v[124:125], v[116:117], v[114:115], v[124:125]
	v_cvt_pk_bf16_f32 v114, v118, v119
	v_cvt_pk_bf16_f32 v115, v120, v121
	v_cvt_pk_bf16_f32 v116, v122, v123
	v_cvt_pk_bf16_f32 v117, v124, v125
	global_store_dwordx4 v[210:211], v[114:117], off offset:256
	s_nop 1
	v_lshlrev_b32_e32 v114, 16, v170
	v_and_b32_e32 v115, 0xffff0000, v170
	s_waitcnt vmcnt(12)
	v_lshlrev_b32_e32 v116, 16, v174
	v_and_b32_e32 v117, 0xffff0000, v174
	v_pk_fma_f32 v[110:111], v[110:111], v[114:115], v[116:117]
	v_lshlrev_b32_e32 v114, 16, v171
	v_and_b32_e32 v115, 0xffff0000, v171
	v_lshlrev_b32_e32 v116, 16, v175
	v_and_b32_e32 v117, 0xffff0000, v175
	v_pk_fma_f32 v[112:113], v[112:113], v[114:115], v[116:117]
	v_lshlrev_b32_e32 v114, 16, v172
	v_and_b32_e32 v115, 0xffff0000, v172
	v_lshlrev_b32_e32 v116, 16, v176
	v_and_b32_e32 v117, 0xffff0000, v176
	v_pk_fma_f32 v[114:115], v[106:107], v[114:115], v[116:117]
	v_lshlrev_b32_e32 v106, 16, v173
	v_and_b32_e32 v107, 0xffff0000, v173
	v_lshlrev_b32_e32 v116, 16, v177
	v_and_b32_e32 v117, 0xffff0000, v177
	v_pk_fma_f32 v[116:117], v[108:109], v[106:107], v[116:117]
	v_cvt_pk_bf16_f32 v106, v110, v111
	v_cvt_pk_bf16_f32 v107, v112, v113
	v_cvt_pk_bf16_f32 v108, v114, v115
	v_cvt_pk_bf16_f32 v109, v116, v117
	global_store_dwordx4 v[208:209], v[106:109], off
	s_waitcnt vmcnt(12)
	s_nop 0
	v_lshlrev_b32_e32 v106, 16, v166
	v_and_b32_e32 v107, 0xffff0000, v166
	s_waitcnt vmcnt(11)
	v_lshlrev_b32_e32 v108, 16, v162
	v_and_b32_e32 v109, 0xffff0000, v162
	v_pk_fma_f32 v[102:103], v[102:103], v[106:107], v[108:109]
	v_lshlrev_b32_e32 v106, 16, v167
	v_and_b32_e32 v107, 0xffff0000, v167
	v_lshlrev_b32_e32 v108, 16, v163
	v_and_b32_e32 v109, 0xffff0000, v163
	v_pk_fma_f32 v[104:105], v[104:105], v[106:107], v[108:109]
	v_lshlrev_b32_e32 v106, 16, v168
	v_and_b32_e32 v107, 0xffff0000, v168
	v_lshlrev_b32_e32 v108, 16, v164
	v_and_b32_e32 v109, 0xffff0000, v164
	v_pk_fma_f32 v[106:107], v[98:99], v[106:107], v[108:109]
	v_lshlrev_b32_e32 v98, 16, v169
	v_and_b32_e32 v99, 0xffff0000, v169
	v_lshlrev_b32_e32 v108, 16, v165
	v_and_b32_e32 v109, 0xffff0000, v165
	v_pk_fma_f32 v[108:109], v[100:101], v[98:99], v[108:109]
	v_cvt_pk_bf16_f32 v98, v102, v103
	v_cvt_pk_bf16_f32 v99, v104, v105
	v_cvt_pk_bf16_f32 v100, v106, v107
	v_cvt_pk_bf16_f32 v101, v108, v109
	global_store_dwordx4 v[208:209], v[98:101], off offset:256
	s_waitcnt vmcnt(11)
	s_nop 0
	v_lshlrev_b32_e32 v98, 16, v154
	v_and_b32_e32 v99, 0xffff0000, v154
	s_waitcnt vmcnt(10)
	v_lshlrev_b32_e32 v100, 16, v158
	v_and_b32_e32 v101, 0xffff0000, v158
	v_pk_fma_f32 v[94:95], v[94:95], v[98:99], v[100:101]
	v_lshlrev_b32_e32 v98, 16, v155
	v_and_b32_e32 v99, 0xffff0000, v155
	v_lshlrev_b32_e32 v100, 16, v159
	v_and_b32_e32 v101, 0xffff0000, v159
	v_pk_fma_f32 v[96:97], v[96:97], v[98:99], v[100:101]
	v_lshlrev_b32_e32 v98, 16, v156
	v_and_b32_e32 v99, 0xffff0000, v156
	v_lshlrev_b32_e32 v100, 16, v160
	v_and_b32_e32 v101, 0xffff0000, v160
	v_pk_fma_f32 v[98:99], v[90:91], v[98:99], v[100:101]
	v_lshlrev_b32_e32 v90, 16, v157
	v_and_b32_e32 v91, 0xffff0000, v157
	v_lshlrev_b32_e32 v100, 16, v161
	v_and_b32_e32 v101, 0xffff0000, v161
	v_pk_fma_f32 v[100:101], v[92:93], v[90:91], v[100:101]
	v_cvt_pk_bf16_f32 v90, v94, v95
	v_cvt_pk_bf16_f32 v91, v96, v97
	v_cvt_pk_bf16_f32 v92, v98, v99
	v_cvt_pk_bf16_f32 v93, v100, v101
	global_store_dwordx4 v[206:207], v[90:93], off
	s_waitcnt vmcnt(10)
	s_nop 0
	v_lshlrev_b32_e32 v90, 16, v150
	v_and_b32_e32 v91, 0xffff0000, v150
	s_waitcnt vmcnt(9)
; __device__ __forceinline__ float bflo(unsigned w) { return __uint_as_float(w << 16); }
; __device__ __forceinline__ float bfhi(unsigned w) { return __uint_as_float(w & 0xffff0000u); }
; __device__ __forceinline__ u32x4 pack8(f32x4 a, f32x4 b) { u32x4 w; w.x = cvtpk(a[0], a[1]); w.y = cvtpk(a[2], a[3]); w.z = cvtpk(b[0], b[1]); w.w = cvtpk(b[2], b[3]); return w; }
;     __device__ __forceinline__ void operator()(const pg8::f32x4 (&acc)[2][2][4][2], const pg8::Unit& u, int wr, int wc, int fr, int fq) const {
;     ...
;             u32x4 sv[4][2], av[4][2];
;             const size_t off0 = (size_t)(u.pm * 256 + ai * 128 + wr * 64 + fr) * 1024 + u.pn * 256 + wc * 32 + 8 * fq;
; #pragma unroll
;             for (int m = 0; m < 4; ++m)
; #pragma unroll
;                 for (int bj = 0; bj < 2; ++bj) { sv[m][bj] = *(const u32x4*)(S + off0 + (size_t)m * 16 * 1024 + bj * 128); if (ADD) av[m][bj] = *(const u32x4*)(A + off0 + (size_t)m * 16 * 1024 + bj * 128); }
; #pragma unroll
;             for (int m = 0; m < 4; ++m)
; #pragma unroll
;                 for (int bj = 0; bj < 2; ++bj) {
;                     const u32x4 s = sv[m][bj];
;                     f32x4 v0 = acc[ai][bj][m][0], v1 = acc[ai][bj][m][1];
;                     v0[0] *= bflo(s.x); v0[1] *= bfhi(s.x); v0[2] *= bflo(s.y); v0[3] *= bfhi(s.y); v1[0] *= bflo(s.z); v1[1] *= bfhi(s.z); v1[2] *= bflo(s.w); v1[3] *= bfhi(s.w);
;                     if (ADD) { const u32x4 a = av[m][bj];
;                         v0[0] += bflo(a.x); v0[1] += bfhi(a.x); v0[2] += bflo(a.y); v0[3] += bfhi(a.y); v1[0] += bflo(a.z); v1[1] += bfhi(a.z); v1[2] += bflo(a.w); v1[3] += bfhi(a.w); }
;                     *(u32x4*)(S + off0 + (size_t)m * 16 * 1024 + bj * 128) = pack8(v0, v1);
;                 }
	v_lshlrev_b32_e32 v92, 16, v146
	v_and_b32_e32 v93, 0xffff0000, v146
	v_pk_fma_f32 v[86:87], v[86:87], v[90:91], v[92:93]
	v_lshlrev_b32_e32 v90, 16, v151
	v_and_b32_e32 v91, 0xffff0000, v151
	v_lshlrev_b32_e32 v92, 16, v147
	v_and_b32_e32 v93, 0xffff0000, v147
	v_pk_fma_f32 v[88:89], v[88:89], v[90:91], v[92:93]
	v_lshlrev_b32_e32 v90, 16, v152
	v_and_b32_e32 v91, 0xffff0000, v152
	v_lshlrev_b32_e32 v92, 16, v148
	v_and_b32_e32 v93, 0xffff0000, v148
	v_pk_fma_f32 v[90:91], v[82:83], v[90:91], v[92:93]
	v_lshlrev_b32_e32 v82, 16, v153
	v_and_b32_e32 v83, 0xffff0000, v153
	v_lshlrev_b32_e32 v92, 16, v149
	v_and_b32_e32 v93, 0xffff0000, v149
	v_pk_fma_f32 v[92:93], v[84:85], v[82:83], v[92:93]
	v_cvt_pk_bf16_f32 v82, v86, v87
	v_cvt_pk_bf16_f32 v83, v88, v89
	v_cvt_pk_bf16_f32 v84, v90, v91
	v_cvt_pk_bf16_f32 v85, v92, v93
	global_store_dwordx4 v[206:207], v[82:85], off offset:256
	s_waitcnt vmcnt(9)
	s_nop 0
	v_lshlrev_b32_e32 v82, 16, v138
	v_and_b32_e32 v83, 0xffff0000, v138
	s_waitcnt vmcnt(8)
	v_lshlrev_b32_e32 v84, 16, v142
	v_and_b32_e32 v85, 0xffff0000, v142
	v_pk_fma_f32 v[76:77], v[76:77], v[82:83], v[84:85]
	v_lshlrev_b32_e32 v82, 16, v139
	v_and_b32_e32 v83, 0xffff0000, v139
	v_lshlrev_b32_e32 v84, 16, v143
	v_and_b32_e32 v85, 0xffff0000, v143
	v_pk_fma_f32 v[78:79], v[78:79], v[82:83], v[84:85]
	v_lshlrev_b32_e32 v82, 16, v140
	v_and_b32_e32 v83, 0xffff0000, v140
	v_lshlrev_b32_e32 v84, 16, v144
	v_and_b32_e32 v85, 0xffff0000, v144
	v_pk_fma_f32 v[82:83], v[72:73], v[82:83], v[84:85]
	v_lshlrev_b32_e32 v72, 16, v141
	v_and_b32_e32 v73, 0xffff0000, v141
	v_lshlrev_b32_e32 v84, 16, v145
	v_and_b32_e32 v85, 0xffff0000, v145
	v_pk_fma_f32 v[84:85], v[74:75], v[72:73], v[84:85]
	v_cvt_pk_bf16_f32 v72, v76, v77
	v_cvt_pk_bf16_f32 v73, v78, v79
	v_cvt_pk_bf16_f32 v74, v82, v83
	v_cvt_pk_bf16_f32 v75, v84, v85
	global_store_dwordx4 v[204:205], v[72:75], off
	s_waitcnt vmcnt(8)
	s_nop 0
	v_lshlrev_b32_e32 v72, 16, v134
	v_and_b32_e32 v73, 0xffff0000, v134
	s_waitcnt vmcnt(7)
	v_lshlrev_b32_e32 v74, 16, v130
	v_and_b32_e32 v75, 0xffff0000, v130
	v_pk_fma_f32 v[68:69], v[68:69], v[72:73], v[74:75]
	v_lshlrev_b32_e32 v72, 16, v135
	v_and_b32_e32 v73, 0xffff0000, v135
	v_lshlrev_b32_e32 v74, 16, v131
	v_and_b32_e32 v75, 0xffff0000, v131
	v_pk_fma_f32 v[70:71], v[70:71], v[72:73], v[74:75]
	v_lshlrev_b32_e32 v72, 16, v136
	v_and_b32_e32 v73, 0xffff0000, v136
	v_lshlrev_b32_e32 v74, 16, v132
	v_and_b32_e32 v75, 0xffff0000, v132
	v_pk_fma_f32 v[72:73], v[64:65], v[72:73], v[74:75]
	v_lshlrev_b32_e32 v64, 16, v137
	v_and_b32_e32 v65, 0xffff0000, v137
	v_lshlrev_b32_e32 v74, 16, v133
	v_and_b32_e32 v75, 0xffff0000, v133
	v_pk_fma_f32 v[74:75], v[66:67], v[64:65], v[74:75]
	v_cvt_pk_bf16_f32 v64, v68, v69
	v_cvt_pk_bf16_f32 v65, v70, v71
	v_cvt_pk_bf16_f32 v66, v72, v73
	v_cvt_pk_bf16_f32 v67, v74, v75
	global_store_dwordx4 v[204:205], v[64:67], off offset:256
	s_nop 1
	v_add_u32_e32 v64, 0x80, v200
	v_ashrrev_i32_e32 v65, 31, v64
	v_lshlrev_b64 v[64:65], 10, v[64:65]
	v_lshl_add_u64 v[64:65], v[64:65], 0, v[202:203]
	v_lshlrev_b64 v[64:65], 1, v[64:65]
	v_lshl_add_u64 v[136:137], s[84:85], 0, v[64:65]
	v_lshl_add_u64 v[64:65], s[80:81], 0, v[64:65]
	global_load_dwordx4 v[104:107], v[136:137], off
	global_load_dwordx4 v[108:111], v[64:65], off
	global_load_dwordx4 v[112:115], v[136:137], off offset:256
	global_load_dwordx4 v[116:119], v[64:65], off offset:256
	v_add_co_u32_e32 v102, vcc, s11, v136
	s_nop 0
	v_addc_co_u32_e32 v103, vcc, 0, v137, vcc
	global_load_dwordx4 v[120:123], v[102:103], off
	v_add_co_u32_e32 v66, vcc, s11, v64
	s_nop 0
	v_addc_co_u32_e32 v67, vcc, 0, v65, vcc
	global_load_dwordx4 v[124:127], v[66:67], off
	global_load_dwordx4 v[128:131], v[102:103], off offset:256
	global_load_dwordx4 v[132:135], v[66:67], off offset:256
	v_add_co_u32_e32 v100, vcc, s33, v136
	s_nop 0
	v_addc_co_u32_e32 v101, vcc, 0, v137, vcc
	global_load_dwordx4 v[90:93], v[100:101], off
	v_add_co_u32_e32 v66, vcc, s33, v64
	s_nop 0
	v_addc_co_u32_e32 v67, vcc, 0, v65, vcc
	global_load_dwordx4 v[94:97], v[66:67], off
	global_load_dwordx4 v[86:89], v[100:101], off offset:256
	global_load_dwordx4 v[82:85], v[66:67], off offset:256
	v_add_co_u32_e32 v98, vcc, s10, v136
	s_nop 0
	v_addc_co_u32_e32 v99, vcc, 0, v137, vcc
	global_load_dwordx4 v[72:75], v[98:99], off
	v_add_co_u32_e32 v64, vcc, s10, v64
	s_nop 0
	v_addc_co_u32_e32 v65, vcc, 0, v65, vcc
	global_load_dwordx4 v[76:79], v[64:65], off
	global_load_dwordx4 v[68:71], v[98:99], off offset:256
	s_nop 0
	global_load_dwordx4 v[64:67], v[64:65], off offset:256
	s_waitcnt vmcnt(15)
	v_lshlrev_b32_e32 v138, 16, v104
	v_and_b32_e32 v139, 0xffff0000, v104
	s_waitcnt vmcnt(14)
	v_lshlrev_b32_e32 v140, 16, v108
	v_and_b32_e32 v141, 0xffff0000, v108
	v_lshlrev_b32_e32 v104, 16, v105
	v_and_b32_e32 v105, 0xffff0000, v105
	v_lshlrev_b32_e32 v108, 16, v109
	v_and_b32_e32 v109, 0xffff0000, v109
	v_pk_fma_f32 v[62:63], v[62:63], v[104:105], v[108:109]
	v_lshlrev_b32_e32 v104, 16, v106
	v_and_b32_e32 v105, 0xffff0000, v106
	v_lshlrev_b32_e32 v108, 16, v110
	v_and_b32_e32 v109, 0xffff0000, v110
	v_pk_fma_f32 v[104:105], v[56:57], v[104:105], v[108:109]
	v_lshlrev_b32_e32 v56, 16, v107
	v_and_b32_e32 v57, 0xffff0000, v107
	v_lshlrev_b32_e32 v106, 16, v111
	v_and_b32_e32 v107, 0xffff0000, v111
	v_pk_fma_f32 v[60:61], v[60:61], v[138:139], v[140:141]
	v_pk_fma_f32 v[106:107], v[58:59], v[56:57], v[106:107]
	v_cvt_pk_bf16_f32 v56, v60, v61
	v_cvt_pk_bf16_f32 v57, v62, v63
	v_cvt_pk_bf16_f32 v58, v104, v105
	v_cvt_pk_bf16_f32 v59, v106, v107
	global_store_dwordx4 v[136:137], v[56:59], off
	s_andn2_b64 vcc, exec, s[38:39]
	s_waitcnt vmcnt(14)
; __device__ __forceinline__ float bflo(unsigned w) { return __uint_as_float(w << 16); }
; __device__ __forceinline__ float bfhi(unsigned w) { return __uint_as_float(w & 0xffff0000u); }
; __device__ __forceinline__ u32x4 pack8(f32x4 a, f32x4 b) { u32x4 w; w.x = cvtpk(a[0], a[1]); w.y = cvtpk(a[2], a[3]); w.z = cvtpk(b[0], b[1]); w.w = cvtpk(b[2], b[3]); return w; }
;     __device__ __forceinline__ void operator()(const pg8::f32x4 (&acc)[2][2][4][2], const pg8::Unit& u, int wr, int wc, int fr, int fq) const {
;     ...
;             for (int m = 0; m < 4; ++m)
; #pragma unroll
;                 for (int bj = 0; bj < 2; ++bj) {
;                     const u32x4 s = sv[m][bj];
;                     f32x4 v0 = acc[ai][bj][m][0], v1 = acc[ai][bj][m][1];
;                     v0[0] *= bflo(s.x); v0[1] *= bfhi(s.x); v0[2] *= bflo(s.y); v0[3] *= bfhi(s.y); v1[0] *= bflo(s.z); v1[1] *= bfhi(s.z); v1[2] *= bflo(s.w); v1[3] *= bfhi(s.w);
;                     if (ADD) { const u32x4 a = av[m][bj];
;                         v0[0] += bflo(a.x); v0[1] += bfhi(a.x); v0[2] += bflo(a.y); v0[3] += bfhi(a.y); v1[0] += bflo(a.z); v1[1] += bfhi(a.z); v1[2] += bflo(a.w); v1[3] += bfhi(a.w); }
;                     *(u32x4*)(S + off0 + (size_t)m * 16 * 1024 + bj * 128) = pack8(v0, v1);
;                 }
	v_lshlrev_b32_e32 v56, 16, v112
	v_and_b32_e32 v57, 0xffff0000, v112
	s_waitcnt vmcnt(13)
	v_lshlrev_b32_e32 v58, 16, v116
	v_and_b32_e32 v59, 0xffff0000, v116
	v_pk_fma_f32 v[52:53], v[52:53], v[56:57], v[58:59]
	v_lshlrev_b32_e32 v56, 16, v113
	v_and_b32_e32 v57, 0xffff0000, v113
	v_lshlrev_b32_e32 v58, 16, v117
	v_and_b32_e32 v59, 0xffff0000, v117
	v_pk_fma_f32 v[54:55], v[54:55], v[56:57], v[58:59]
	v_lshlrev_b32_e32 v56, 16, v114
	v_and_b32_e32 v57, 0xffff0000, v114
	v_lshlrev_b32_e32 v58, 16, v118
	v_and_b32_e32 v59, 0xffff0000, v118
	v_pk_fma_f32 v[56:57], v[48:49], v[56:57], v[58:59]
	v_lshlrev_b32_e32 v48, 16, v115
	v_and_b32_e32 v49, 0xffff0000, v115
	v_lshlrev_b32_e32 v58, 16, v119
	v_and_b32_e32 v59, 0xffff0000, v119
	v_pk_fma_f32 v[58:59], v[50:51], v[48:49], v[58:59]
	v_cvt_pk_bf16_f32 v48, v52, v53
	v_cvt_pk_bf16_f32 v49, v54, v55
	v_cvt_pk_bf16_f32 v50, v56, v57
	v_cvt_pk_bf16_f32 v51, v58, v59
	global_store_dwordx4 v[136:137], v[48:51], off offset:256
	s_waitcnt vmcnt(13)
	s_nop 0
	v_lshlrev_b32_e32 v48, 16, v120
	v_and_b32_e32 v49, 0xffff0000, v120
	s_waitcnt vmcnt(12)
	v_lshlrev_b32_e32 v50, 16, v124
	v_and_b32_e32 v51, 0xffff0000, v124
	v_pk_fma_f32 v[44:45], v[44:45], v[48:49], v[50:51]
	v_lshlrev_b32_e32 v48, 16, v121
	v_and_b32_e32 v49, 0xffff0000, v121
	v_lshlrev_b32_e32 v50, 16, v125
	v_and_b32_e32 v51, 0xffff0000, v125
	v_pk_fma_f32 v[46:47], v[46:47], v[48:49], v[50:51]
	v_lshlrev_b32_e32 v48, 16, v122
	v_and_b32_e32 v49, 0xffff0000, v122
	v_lshlrev_b32_e32 v50, 16, v126
	v_and_b32_e32 v51, 0xffff0000, v126
	v_pk_fma_f32 v[48:49], v[40:41], v[48:49], v[50:51]
	v_lshlrev_b32_e32 v40, 16, v123
	v_and_b32_e32 v41, 0xffff0000, v123
	v_lshlrev_b32_e32 v50, 16, v127
	v_and_b32_e32 v51, 0xffff0000, v127
	v_pk_fma_f32 v[50:51], v[42:43], v[40:41], v[50:51]
	v_cvt_pk_bf16_f32 v40, v44, v45
	v_cvt_pk_bf16_f32 v41, v46, v47
	v_cvt_pk_bf16_f32 v42, v48, v49
	v_cvt_pk_bf16_f32 v43, v50, v51
	global_store_dwordx4 v[102:103], v[40:43], off
	s_waitcnt vmcnt(12)
	s_nop 0
	v_lshlrev_b32_e32 v40, 16, v128
	v_and_b32_e32 v41, 0xffff0000, v128
	s_waitcnt vmcnt(11)
	v_lshlrev_b32_e32 v42, 16, v132
	v_and_b32_e32 v43, 0xffff0000, v132
	v_pk_fma_f32 v[36:37], v[36:37], v[40:41], v[42:43]
	v_lshlrev_b32_e32 v40, 16, v129
	v_and_b32_e32 v41, 0xffff0000, v129
	v_lshlrev_b32_e32 v42, 16, v133
	v_and_b32_e32 v43, 0xffff0000, v133
	v_pk_fma_f32 v[38:39], v[38:39], v[40:41], v[42:43]
	v_lshlrev_b32_e32 v40, 16, v130
	v_and_b32_e32 v41, 0xffff0000, v130
	v_lshlrev_b32_e32 v42, 16, v134
	v_and_b32_e32 v43, 0xffff0000, v134
	v_pk_fma_f32 v[40:41], v[32:33], v[40:41], v[42:43]
	v_lshlrev_b32_e32 v32, 16, v131
	v_and_b32_e32 v33, 0xffff0000, v131
	v_lshlrev_b32_e32 v42, 16, v135
	v_and_b32_e32 v43, 0xffff0000, v135
	v_pk_fma_f32 v[42:43], v[34:35], v[32:33], v[42:43]
	v_cvt_pk_bf16_f32 v32, v36, v37
	v_cvt_pk_bf16_f32 v33, v38, v39
	v_cvt_pk_bf16_f32 v34, v40, v41
	v_cvt_pk_bf16_f32 v35, v42, v43
	global_store_dwordx4 v[102:103], v[32:35], off offset:256
	s_waitcnt vmcnt(11)
	s_nop 0
	v_lshlrev_b32_e32 v32, 16, v90
	v_and_b32_e32 v33, 0xffff0000, v90
	s_waitcnt vmcnt(10)
	v_lshlrev_b32_e32 v34, 16, v94
	v_and_b32_e32 v35, 0xffff0000, v94
	v_pk_fma_f32 v[28:29], v[28:29], v[32:33], v[34:35]
	v_lshlrev_b32_e32 v32, 16, v91
	v_and_b32_e32 v33, 0xffff0000, v91
	v_lshlrev_b32_e32 v34, 16, v95
	v_and_b32_e32 v35, 0xffff0000, v95
	v_pk_fma_f32 v[30:31], v[30:31], v[32:33], v[34:35]
	v_lshlrev_b32_e32 v32, 16, v92
	v_and_b32_e32 v33, 0xffff0000, v92
	v_lshlrev_b32_e32 v34, 16, v96
	v_and_b32_e32 v35, 0xffff0000, v96
	v_pk_fma_f32 v[32:33], v[24:25], v[32:33], v[34:35]
	v_lshlrev_b32_e32 v24, 16, v93
	v_and_b32_e32 v25, 0xffff0000, v93
	v_lshlrev_b32_e32 v34, 16, v97
	v_and_b32_e32 v35, 0xffff0000, v97
	v_pk_fma_f32 v[34:35], v[26:27], v[24:25], v[34:35]
	v_cvt_pk_bf16_f32 v24, v28, v29
	v_cvt_pk_bf16_f32 v25, v30, v31
	v_cvt_pk_bf16_f32 v26, v32, v33
	v_cvt_pk_bf16_f32 v27, v34, v35
	global_store_dwordx4 v[100:101], v[24:27], off
	s_waitcnt vmcnt(10)
	s_nop 0
	v_lshlrev_b32_e32 v24, 16, v86
	v_and_b32_e32 v25, 0xffff0000, v86
	s_waitcnt vmcnt(9)
	v_lshlrev_b32_e32 v26, 16, v82
	v_and_b32_e32 v27, 0xffff0000, v82
	v_pk_fma_f32 v[20:21], v[20:21], v[24:25], v[26:27]
	v_lshlrev_b32_e32 v24, 16, v87
	v_and_b32_e32 v25, 0xffff0000, v87
	v_lshlrev_b32_e32 v26, 16, v83
	v_and_b32_e32 v27, 0xffff0000, v83
	v_pk_fma_f32 v[22:23], v[22:23], v[24:25], v[26:27]
	v_lshlrev_b32_e32 v24, 16, v88
	v_and_b32_e32 v25, 0xffff0000, v88
	v_lshlrev_b32_e32 v26, 16, v84
	v_and_b32_e32 v27, 0xffff0000, v84
	v_pk_fma_f32 v[24:25], v[16:17], v[24:25], v[26:27]
	v_lshlrev_b32_e32 v16, 16, v89
	v_and_b32_e32 v17, 0xffff0000, v89
	v_lshlrev_b32_e32 v26, 16, v85
	v_and_b32_e32 v27, 0xffff0000, v85
	v_pk_fma_f32 v[26:27], v[18:19], v[16:17], v[26:27]
	v_cvt_pk_bf16_f32 v16, v20, v21
	v_cvt_pk_bf16_f32 v17, v22, v23
	v_cvt_pk_bf16_f32 v18, v24, v25
	v_cvt_pk_bf16_f32 v19, v26, v27
	global_store_dwordx4 v[100:101], v[16:19], off offset:256
	s_waitcnt vmcnt(9)
	s_nop 0
	v_lshlrev_b32_e32 v16, 16, v72
	v_and_b32_e32 v17, 0xffff0000, v72
	s_waitcnt vmcnt(8)
	v_lshlrev_b32_e32 v18, 16, v76
	v_and_b32_e32 v19, 0xffff0000, v76
	v_pk_fma_f32 v[12:13], v[12:13], v[16:17], v[18:19]
	v_lshlrev_b32_e32 v16, 16, v73
	v_and_b32_e32 v17, 0xffff0000, v73
	v_lshlrev_b32_e32 v18, 16, v77
	v_and_b32_e32 v19, 0xffff0000, v77
	v_pk_fma_f32 v[14:15], v[14:15], v[16:17], v[18:19]
	v_lshlrev_b32_e32 v16, 16, v74
	v_and_b32_e32 v17, 0xffff0000, v74
	v_lshlrev_b32_e32 v18, 16, v78
	v_and_b32_e32 v19, 0xffff0000, v78
	v_pk_fma_f32 v[16:17], v[8:9], v[16:17], v[18:19]
	v_lshlrev_b32_e32 v8, 16, v75
	v_and_b32_e32 v9, 0xffff0000, v75
	v_lshlrev_b32_e32 v18, 16, v79
	v_and_b32_e32 v19, 0xffff0000, v79
	v_pk_fma_f32 v[18:19], v[10:11], v[8:9], v[18:19]
	v_cvt_pk_bf16_f32 v8, v12, v13
	v_cvt_pk_bf16_f32 v9, v14, v15
	v_cvt_pk_bf16_f32 v10, v16, v17
	v_cvt_pk_bf16_f32 v11, v18, v19
	global_store_dwordx4 v[98:99], v[8:11], off
	s_waitcnt vmcnt(8)
	s_nop 0
	v_lshlrev_b32_e32 v8, 16, v68
	v_and_b32_e32 v9, 0xffff0000, v68
	s_waitcnt vmcnt(7)
	v_lshlrev_b32_e32 v10, 16, v64
	v_and_b32_e32 v11, 0xffff0000, v64
	v_pk_fma_f32 v[4:5], v[4:5], v[8:9], v[10:11]
	v_lshlrev_b32_e32 v8, 16, v69
	v_and_b32_e32 v9, 0xffff0000, v69
	v_lshlrev_b32_e32 v10, 16, v65
	v_and_b32_e32 v11, 0xffff0000, v65
	v_pk_fma_f32 v[6:7], v[6:7], v[8:9], v[10:11]
	v_lshlrev_b32_e32 v8, 16, v70
	v_and_b32_e32 v9, 0xffff0000, v70
	v_lshlrev_b32_e32 v10, 16, v66
	v_and_b32_e32 v11, 0xffff0000, v66
	v_pk_fma_f32 v[8:9], v[0:1], v[8:9], v[10:11]
	v_lshlrev_b32_e32 v0, 16, v71
	v_and_b32_e32 v1, 0xffff0000, v71
	v_lshlrev_b32_e32 v10, 16, v67
	v_and_b32_e32 v11, 0xffff0000, v67
	v_pk_fma_f32 v[10:11], v[2:3], v[0:1], v[10:11]
	v_cvt_pk_bf16_f32 v0, v4, v5
	v_cvt_pk_bf16_f32 v1, v6, v7
	v_cvt_pk_bf16_f32 v2, v8, v9
	v_cvt_pk_bf16_f32 v3, v10, v11
	global_store_dwordx4 v[98:99], v[0:3], off offset:256
	s_cbranch_vccnz .LBB0_1332
	s_andn2_b64 vcc, exec, s[4:5]
	s_cbranch_vccnz .LBB0_1331
	s_barrier
	s_branch .LBB0_1331
